# out-proj GEMM epilogue: 16 residual quads loaded together (one wait) instead of 16 load-fma-store round trips; prep tile per-column constants loaded at tile start
# speedup vs baseline: 1.0503x; 1.0183x over previous
; __device__ __forceinline__ int launder(int x) { asm volatile("" : "+v"(x)); return x; }
; __device__ __forceinline__ void rwkv_prep_tile(const Params& p, int l, int tile, unsigned char* smem) {
;   const int d = tile & 1, tb = (tile >> 1) % 136, b = tile / 272;
;   bf16_t* raw = (bf16_t*)smem;
;   bf16_t* Aw = raw + 34 * 384;
;   bf16_t* Aa = Aw + 32 * 72;
;   const int tid = launder(threadIdx.x), lane = tid & 63, w = tid >> 6, fr = lane & 15, fq = lane >> 4;
;   const int p0 = tb * 32;
;   const int slo = (p0 < 256) ? 0 : 256, shi = (p0 < 256) ? 255 : 4351;
;   const size_t rowbase = (size_t)b * TPB;
;   const int ld2 = l * 2 + d;
;   for (int q = tid; q < 34 * 48; q += 256) {
.LBB0_815:
	v_mov_b32_e32 v72, v189
	s_movk_i32 s42, 0x65f
	s_and_b32 s28, s47, 1
	s_nop 0
	v_cmp_lt_i32_e32 vcc, s42, v72
	s_and_saveexec_b64 s[42:43], vcc
	s_xor_b64 s[42:43], exec, s[42:43]
	s_lshl_b32 s58, s28, 6
	s_or_saveexec_b64 s[56:57], s[42:43]
	s_ashr_i32 s42, s47, 1
	s_mul_hi_i32 s43, s42, 0x78787879
	s_lshr_b32 s44, s43, 31
	s_ashr_i32 s43, s43, 6
	s_add_i32 s43, s43, s44
	s_mulk_i32 s43, 0x88
	s_sub_i32 s42, s42, s43
	s_mul_hi_i32 s43, s47, 0x78787879
	s_lshr_b32 s44, s43, 31
	s_ashr_i32 s43, s43, 7
	s_add_i32 s43, s43, s44
	s_lshl_b32 s62, s42, 5
	s_mul_hi_i32 s45, s43, 0x1100
	s_mul_i32 s44, s43, 0x1100
	v_mov_b32_e32 v1, s58
	s_xor_b64 exec, exec, s[56:57]
	s_cbranch_execz .LBB0_832
; __device__ __forceinline__ void rwkv_prep_tile(const Params& p, int l, int tile, unsigned char* smem) {
;     ...
;   for (int q = tid; q < 34 * 48; q += 256) {
;     const int rr = q / 48, cc = q % 48;
;     const int tr = p0 - 1 + rr;
;     const int col = (cc < 32) ? (256 + cc * 8) : ((cc < 40) ? (768 + d * 64 + (cc - 32) * 8) : (896 + d * 64 + (cc - 40) * 8));
;     uint4 v = make_uint4(0, 0, 0, 0);
;     if (tr >= slo && tr <= shi) v = *(const uint4*)(p.PR + (rowbase + tr) * 1024 + col);
;     *(uint4*)(raw + rr * 384 + cc * 8) = v;
;   }
;   __syncthreads();
;   const float* mu0 = p.rwkv_mu + (size_t)(l * 2 + 0) * 1024;
;   const float* mu1 = p.rwkv_mu + (size_t)(l * 2 + 1) * 1024;
;   {
;     const int ca = tid & 63;
;     const float m0wd = mu0[768 + d * 64 + ca], m1wd = mu1[768 + d * 64 + ca];
;     const float m0ad = mu0[896 + d * 64 + ca], m1ad = mu1[896 + d * 64 + ca];
;     ...
;   for (int nt = 0; nt < 4; ++nt) {
;     const int c = w * 64 + nt * 16 + fr;
;     const float m0k = mu0[256 + c], m1k = mu1[256 + c], kkc = p.rwkv_k_k[ld2 * 256 + c];
	s_cmp_lt_i32 s42, 8
	s_movk_i32 s0, 0x10ff
	s_cselect_b32 s63, 0, 0x100
	s_cselect_b32 s65, 0xff, s0
	s_lshl_b32 s64, s28, 6
	s_add_i32 s66, s62, -1
	v_readlane_b32 s10, v251, 58
	v_readlane_b32 s11, v251, 59
	s_lshl_b32 s67, s28, 7
	s_add_i32 s68, s67, 0x480
	s_addk_i32 s67, 0x400
	s_mov_b32 s1, 0x5555556
	s_movk_i32 s12, 0x660
	v_and_b32_e32 v0, 63, v72
	v_or_b32_e32 v5, s64, v0
	v_lshlrev_b32_e32 v5, 2, v5
	global_load_dword v1, v5, s[52:53] offset:3072
	global_load_dword v2, v5, s[54:55] offset:3072
	global_load_dword v3, v5, s[54:55] offset:3584
	global_load_dword v4, v5, s[52:53] offset:3584
	v_readlane_b32 s14, v251, 14
	v_readlane_b32 s15, v251, 15
	v_and_b32_e32 v108, 0xffffffcf, v72
	v_lshlrev_b32_e32 v108, 2, v108
	s_or_b32 s13, s28, s46
	s_lshl_b32 s13, s13, 10
	v_add_u32_e32 v109, s13, v108
	global_load_dword v118, v108, s[52:53] offset:1024
	global_load_dword v119, v108, s[54:55] offset:1024
	global_load_dword v121, v108, s[52:53] offset:1088
	global_load_dword v122, v108, s[54:55] offset:1088
	global_load_dword v123, v108, s[54:55] offset:1152
	global_load_dword v124, v108, s[52:53] offset:1152
	global_load_dword v127, v108, s[52:53] offset:1216
	global_load_dword v128, v108, s[54:55] offset:1216
	global_load_dword v120, v109, s[14:15]
	global_load_dword v125, v109, s[14:15] offset:64
	global_load_dword v126, v109, s[14:15] offset:128
	global_load_dword v129, v109, s[14:15] offset:192
	v_mov_b32_e32 v40, 0x200
	v_mov_b32_e32 v41, s67
	v_mov_b32_e32 v42, s68
	v_mov_b32_e32 v6, v72
	v_mul_hi_u32 v7, v6, s1
	v_mul_u32_u24_e32 v8, 48, v7
	v_sub_u32_e32 v8, v6, v8
	v_add_u32_e32 v9, s66, v7
	v_cmp_le_i32_e32 vcc, s63, v9
	v_cmp_ge_i32_e64 s[2:3], s65, v9
	v_cmp_lt_u32_e64 s[4:5], 31, v8
	v_cmp_lt_u32_e64 s[6:7], 39, v8
	v_add_u32_e32 v9, s44, v9
	v_lshlrev_b32_e32 v9, 11, v9
	v_lshl_add_u32 v9, v8, 4, v9
	v_cndmask_b32_e64 v10, v40, v41, s[4:5]
	v_cndmask_b32_e64 v10, v10, v42, s[6:7]
	v_add_u32_e32 v9, v9, v10
	s_and_b64 s[2:3], vcc, s[2:3]
	v_mov_b32_e32 v80, 0
	v_mov_b32_e32 v81, 0
	v_mov_b32_e32 v82, 0
	v_mov_b32_e32 v83, 0
	s_and_saveexec_b64 s[58:59], s[2:3]
	global_load_dwordx4 v[80:83], v9, s[10:11]
	s_mov_b64 exec, s[58:59]
	v_add_u32_e32 v6, 0x100, v72
	v_mul_hi_u32 v7, v6, s1
	v_mul_u32_u24_e32 v8, 48, v7
	v_sub_u32_e32 v8, v6, v8
	v_add_u32_e32 v9, s66, v7
	v_cmp_le_i32_e32 vcc, s63, v9
	v_cmp_ge_i32_e64 s[2:3], s65, v9
	v_cmp_lt_u32_e64 s[4:5], 31, v8
	v_cmp_lt_u32_e64 s[6:7], 39, v8
	v_add_u32_e32 v9, s44, v9
	v_lshlrev_b32_e32 v9, 11, v9
	v_lshl_add_u32 v9, v8, 4, v9
	v_cndmask_b32_e64 v10, v40, v41, s[4:5]
	v_cndmask_b32_e64 v10, v10, v42, s[6:7]
	v_add_u32_e32 v9, v9, v10
	s_and_b64 s[2:3], vcc, s[2:3]
	v_mov_b32_e32 v84, 0
	v_mov_b32_e32 v85, 0
	v_mov_b32_e32 v86, 0
	v_mov_b32_e32 v87, 0
	s_and_saveexec_b64 s[58:59], s[2:3]
	global_load_dwordx4 v[84:87], v9, s[10:11]
	s_mov_b64 exec, s[58:59]
	v_add_u32_e32 v6, 0x200, v72
	v_mul_hi_u32 v7, v6, s1
	v_mul_u32_u24_e32 v8, 48, v7
	v_sub_u32_e32 v8, v6, v8
	v_add_u32_e32 v9, s66, v7
	v_cmp_le_i32_e32 vcc, s63, v9
	v_cmp_ge_i32_e64 s[2:3], s65, v9
	v_cmp_lt_u32_e64 s[4:5], 31, v8
	v_cmp_lt_u32_e64 s[6:7], 39, v8
	v_add_u32_e32 v9, s44, v9
	v_lshlrev_b32_e32 v9, 11, v9
	v_lshl_add_u32 v9, v8, 4, v9
	v_cndmask_b32_e64 v10, v40, v41, s[4:5]
	v_cndmask_b32_e64 v10, v10, v42, s[6:7]
	v_add_u32_e32 v9, v9, v10
	s_and_b64 s[2:3], vcc, s[2:3]
	v_mov_b32_e32 v88, 0
	v_mov_b32_e32 v89, 0
	v_mov_b32_e32 v90, 0
	v_mov_b32_e32 v91, 0
	s_and_saveexec_b64 s[58:59], s[2:3]
	global_load_dwordx4 v[88:91], v9, s[10:11]
	s_mov_b64 exec, s[58:59]
	v_add_u32_e32 v6, 0x300, v72
	v_mul_hi_u32 v7, v6, s1
	v_mul_u32_u24_e32 v8, 48, v7
	v_sub_u32_e32 v8, v6, v8
	v_add_u32_e32 v9, s66, v7
	v_cmp_le_i32_e32 vcc, s63, v9
	v_cmp_ge_i32_e64 s[2:3], s65, v9
	v_cmp_lt_u32_e64 s[4:5], 31, v8
	v_cmp_lt_u32_e64 s[6:7], 39, v8
	v_add_u32_e32 v9, s44, v9
	v_lshlrev_b32_e32 v9, 11, v9
	v_lshl_add_u32 v9, v8, 4, v9
	v_cndmask_b32_e64 v10, v40, v41, s[4:5]
	v_cndmask_b32_e64 v10, v10, v42, s[6:7]
	v_add_u32_e32 v9, v9, v10
	s_and_b64 s[2:3], vcc, s[2:3]
	v_mov_b32_e32 v92, 0
	v_mov_b32_e32 v93, 0
	v_mov_b32_e32 v94, 0
	v_mov_b32_e32 v95, 0
	s_and_saveexec_b64 s[58:59], s[2:3]
	global_load_dwordx4 v[92:95], v9, s[10:11]
	s_mov_b64 exec, s[58:59]
	v_add_u32_e32 v6, 0x400, v72
	v_mul_hi_u32 v7, v6, s1
	v_mul_u32_u24_e32 v8, 48, v7
	v_sub_u32_e32 v8, v6, v8
	v_add_u32_e32 v9, s66, v7
	v_cmp_le_i32_e32 vcc, s63, v9
	v_cmp_ge_i32_e64 s[2:3], s65, v9
	v_cmp_lt_u32_e64 s[4:5], 31, v8
	v_cmp_lt_u32_e64 s[6:7], 39, v8
	v_add_u32_e32 v9, s44, v9
	v_lshlrev_b32_e32 v9, 11, v9
	v_lshl_add_u32 v9, v8, 4, v9
	v_cndmask_b32_e64 v10, v40, v41, s[4:5]
	v_cndmask_b32_e64 v10, v10, v42, s[6:7]
	v_add_u32_e32 v9, v9, v10
	s_and_b64 s[2:3], vcc, s[2:3]
	v_mov_b32_e32 v96, 0
	v_mov_b32_e32 v97, 0
	v_mov_b32_e32 v98, 0
	v_mov_b32_e32 v99, 0
	s_and_saveexec_b64 s[58:59], s[2:3]
	global_load_dwordx4 v[96:99], v9, s[10:11]
	s_mov_b64 exec, s[58:59]
	v_add_u32_e32 v6, 0x500, v72
	v_mul_hi_u32 v7, v6, s1
	v_mul_u32_u24_e32 v8, 48, v7
	v_sub_u32_e32 v8, v6, v8
	v_add_u32_e32 v9, s66, v7
	v_cmp_le_i32_e32 vcc, s63, v9
	v_cmp_ge_i32_e64 s[2:3], s65, v9
	v_cmp_lt_u32_e64 s[4:5], 31, v8
	v_cmp_lt_u32_e64 s[6:7], 39, v8
	v_add_u32_e32 v9, s44, v9
	v_lshlrev_b32_e32 v9, 11, v9
	v_lshl_add_u32 v9, v8, 4, v9
	v_cndmask_b32_e64 v10, v40, v41, s[4:5]
	v_cndmask_b32_e64 v10, v10, v42, s[6:7]
	v_add_u32_e32 v9, v9, v10
	s_and_b64 s[2:3], vcc, s[2:3]
	v_mov_b32_e32 v100, 0
	v_mov_b32_e32 v101, 0
	v_mov_b32_e32 v102, 0
	v_mov_b32_e32 v103, 0
	s_and_saveexec_b64 s[58:59], s[2:3]
	global_load_dwordx4 v[100:103], v9, s[10:11]
	s_mov_b64 exec, s[58:59]
	v_add_u32_e32 v6, 0x600, v72
	v_mul_hi_u32 v7, v6, s1
	v_mul_u32_u24_e32 v8, 48, v7
	v_sub_u32_e32 v8, v6, v8
	v_add_u32_e32 v9, s66, v7
	v_cmp_le_i32_e32 vcc, s63, v9
	v_cmp_ge_i32_e64 s[2:3], s65, v9
	v_cmp_lt_u32_e64 s[4:5], 31, v8
	v_cmp_lt_u32_e64 s[6:7], 39, v8
	v_add_u32_e32 v9, s44, v9
	v_lshlrev_b32_e32 v9, 11, v9
	v_lshl_add_u32 v9, v8, 4, v9
	v_cndmask_b32_e64 v10, v40, v41, s[4:5]
	v_cndmask_b32_e64 v10, v10, v42, s[6:7]
	v_add_u32_e32 v9, v9, v10
	s_and_b64 s[2:3], vcc, s[2:3]
	v_cmp_gt_u32_e64 s[8:9], s12, v6
	s_and_b64 s[2:3], s[2:3], s[8:9]
	v_mov_b32_e32 v104, 0
	v_mov_b32_e32 v105, 0
	v_mov_b32_e32 v106, 0
	v_mov_b32_e32 v107, 0
	s_and_saveexec_b64 s[58:59], s[2:3]
	global_load_dwordx4 v[104:107], v9, s[10:11]
	s_mov_b64 exec, s[58:59]
	v_lshlrev_b32_e32 v5, 4, v72
	s_waitcnt vmcnt(0)
	ds_write_b128 v5, v[80:83]
	ds_write_b128 v5, v[84:87] offset:4096
	ds_write_b128 v5, v[88:91] offset:8192
	ds_write_b128 v5, v[92:95] offset:12288
	ds_write_b128 v5, v[96:99] offset:16384
	ds_write_b128 v5, v[100:103] offset:20480
	v_cmp_gt_u32_e32 vcc, s12, v6
	s_and_saveexec_b64 s[58:59], vcc
	ds_write_b128 v5, v[104:107] offset:24576
	s_mov_b64 exec, s[58:59]
	s_branch .LBB0_832

; __device__ __forceinline__ float bf2f(bf16_t v) { return __uint_as_float(((unsigned)v) << 16); }
; __device__ __forceinline__ bf16_t f2bf(float f) { return (bf16_t)(pack2(f, 0.f) & 0xffffu); }
; __device__ __forceinline__ void rwkv_prep_tile(const Params& p, int l, int tile, unsigned char* smem) {
;     ...
; #pragma unroll 2
;     for (int it = 0; it < 8; ++it) {
;       const int i = w + 4 * it;
;       const bf16_t* r0 = raw + (i + 1) * 384 + ca;
;       float u = bf2f(r0[256]), up = bf2f(r0[256 - 384]), un = bf2f(r0[256 + 384]);
;       Aw[i * 72 + ca] = f2bf(tanhf_(u + m0wd * (up - u) + m1wd * (un - u)));
;       u = bf2f(r0[320]); up = bf2f(r0[320 - 384]); un = bf2f(r0[320 + 384]);
;       Aa[i * 72 + ca] = f2bf(u + m0ad * (up - u) + m1ad * (un - u));
;     }
;   }
;     ...
;   for (int nt = 0; nt < 4; ++nt) {
;     const int c = w * 64 + nt * 16 + fr;
;     const float m0k = mu0[256 + c], m1k = mu1[256 + c], kkc = p.rwkv_k_k[ld2 * 256 + c];
; #pragma unroll
;     for (int mt = 0; mt < 2; ++mt)
; #pragma unroll
;       for (int j = 0; j < 4; ++j) {
;         const int i = mt * 16 + fq * 4 + j;
;         const bf16_t* r0 = raw + (i + 1) * 384 + c;
;         const float u = bf2f(r0[0]), up = bf2f(r0[-384]), un = bf2f(r0[384]);
;         const float kq = (u + m0k * (up - u) + m1k * (un - u)) * kkc;
;         kkr[mt][nt][j] = kq;
;         ssq[mt][j] += kq * kq;
.LBB0_833:
	ds_read_u16 v7, v6 offset:768
	ds_read_u16 v8, v6 offset:1536
	ds_read_u16 v9, v6
	v_add_u32_e32 v10, s42, v5
	s_addk_i32 s42, 0x480
	s_waitcnt lgkmcnt(2)
	v_lshlrev_b32_e32 v7, 16, v7
	s_waitcnt lgkmcnt(1)
	v_lshlrev_b32_e32 v8, 16, v8
	s_waitcnt lgkmcnt(0)
	v_lshlrev_b32_e32 v9, 16, v9
	v_sub_f32_e32 v9, v9, v7
	v_sub_f32_e32 v8, v8, v7
	s_waitcnt vmcnt(3)
	v_fmac_f32_e32 v7, v1, v9
	s_waitcnt vmcnt(2)
	v_fmac_f32_e32 v7, v2, v8
	v_add_f32_e32 v7, v7, v7
	v_mul_f32_e32 v7, 0x3fb8aa3b, v7
	v_exp_f32_e32 v7, v7
	s_cmpk_lg_i32 s42, 0x1200
	v_add_f32_e32 v7, 1.0, v7
	v_rcp_f32_e32 v7, v7
	s_nop 0
	v_fma_f32 v7, v7, -2.0, 1.0
	v_cvt_pk_bf16_f32 v7, v7, s0
	ds_write_b16 v10, v7
	ds_read_u16 v7, v6 offset:896
	ds_read_u16 v8, v6 offset:1664
	ds_read_u16 v9, v6 offset:128
	s_waitcnt lgkmcnt(2)
	v_lshlrev_b32_e32 v7, 16, v7
	s_waitcnt lgkmcnt(1)
	v_lshlrev_b32_e32 v8, 16, v8
	s_waitcnt lgkmcnt(0)
	v_lshlrev_b32_e32 v9, 16, v9
	v_sub_f32_e32 v9, v9, v7
	v_sub_f32_e32 v8, v8, v7
	s_waitcnt vmcnt(0)
	v_fmac_f32_e32 v7, v4, v9
	v_fmac_f32_e32 v7, v3, v8
	v_cvt_pk_bf16_f32 v7, v7, s0
	ds_write_b16 v10, v7 offset:4608
	ds_read_u16 v7, v6 offset:3840
	ds_read_u16 v8, v6 offset:4608
	ds_read_u16 v9, v6 offset:3072
	s_waitcnt lgkmcnt(2)
	v_lshlrev_b32_e32 v7, 16, v7
	s_waitcnt lgkmcnt(1)
	v_lshlrev_b32_e32 v8, 16, v8
	s_waitcnt lgkmcnt(0)
	v_lshlrev_b32_e32 v9, 16, v9
	v_sub_f32_e32 v9, v9, v7
	v_sub_f32_e32 v8, v8, v7
	v_fmac_f32_e32 v7, v1, v9
	v_fmac_f32_e32 v7, v2, v8
	v_add_f32_e32 v7, v7, v7
	v_mul_f32_e32 v7, 0x3fb8aa3b, v7
	v_exp_f32_e32 v7, v7
	s_nop 0
	v_add_f32_e32 v7, 1.0, v7
	v_rcp_f32_e32 v7, v7
	s_nop 0
	v_fma_f32 v7, v7, -2.0, 1.0
	v_cvt_pk_bf16_f32 v7, v7, s0
	ds_write_b16 v10, v7 offset:576
	ds_read_u16 v7, v6 offset:3968
	ds_read_u16 v8, v6 offset:4736
	ds_read_u16 v9, v6 offset:3200
	v_add_u32_e32 v6, 0x1800, v6
	s_waitcnt lgkmcnt(2)
	v_lshlrev_b32_e32 v7, 16, v7
	s_waitcnt lgkmcnt(1)
	v_lshlrev_b32_e32 v8, 16, v8
	s_waitcnt lgkmcnt(0)
	v_lshlrev_b32_e32 v9, 16, v9
	v_sub_f32_e32 v9, v9, v7
	v_sub_f32_e32 v8, v8, v7
	v_fmac_f32_e32 v7, v4, v9
	v_fmac_f32_e32 v7, v3, v8
	v_cvt_pk_bf16_f32 v7, v7, s0
	ds_write_b16 v10, v7 offset:5184
	s_cbranch_scc1 .LBB0_833
	s_or_b32 s42, s28, s46
	v_and_b32_e32 v2, 0xffffffcf, v72
	s_lshl_b32 s42, s42, 8
	v_ashrrev_i32_e32 v3, 31, v2
	v_add_u32_e32 v32, s42, v2
	v_lshlrev_b64 v[4:5], 2, v[2:3]
	v_ashrrev_i32_e32 v33, 31, v32
	v_readlane_b32 s64, v251, 0
	v_lshl_add_u64 v[34:35], s[52:53], 0, v[4:5]
	v_lshlrev_b64 v[48:49], 2, v[32:33]
	v_readlane_b32 s78, v251, 14
	v_readlane_b32 s79, v251, 15
	s_waitcnt lgkmcnt(0)
	s_barrier
	v_lshl_add_u64 v[36:37], s[54:55], 0, v[4:5]
	v_mov_b32_e32 v46, v118
	v_mov_b32_e32 v47, v119
	v_lshl_add_u64 v[38:39], s[78:79], 0, v[48:49]
	v_mov_b32_e32 v50, v120
	v_and_b32_e32 v40, 48, v0
	v_lshrrev_b32_e32 v73, 4, v0
	v_and_b32_e32 v1, 15, v72
	v_add_u32_e32 v0, 0, v40
	s_movk_i32 s43, 0xbf0
	v_mul_u32_u24_e32 v1, 0x48, v1
	v_lshlrev_b32_e32 v77, 1, v2
	v_mad_u32_u24 v42, v73, s43, v0
	v_lshlrev_b32_e32 v3, 2, v73
	v_lshl_add_u32 v1, v1, 1, v0
	v_add_u32_e32 v51, v42, v77
	v_or_b32_e32 v41, 16, v3
	v_or_b32_e32 v74, 1, v3
	ds_read_b128 v[28:31], v1 offset:26112
	ds_read_b128 v[24:27], v1 offset:26176
	ds_read_b128 v[20:23], v1 offset:30720
	ds_read_b128 v[16:19], v1 offset:30784
	ds_read_b128 v[12:15], v1 offset:28416
	ds_read_b128 v[8:11], v1 offset:28480
	ds_read_b128 v[4:7], v1 offset:33024
	ds_read_b128 v[0:3], v1 offset:33088
	v_mov_b32_e32 v52, v121
	v_mov_b32_e32 v53, v122
	v_mov_b32_e32 v54, v123
	v_mov_b32_e32 v55, v124
	ds_read_u16 v34, v51 offset:768
	ds_read_u16 v35, v51
	ds_read_u16 v36, v51 offset:32
	ds_read_u16 v37, v51 offset:1536
	ds_read_u16 v56, v51 offset:800
	ds_read_u16 v57, v51 offset:1568
	ds_read_u16 v58, v51 offset:832
	ds_read_u16 v59, v51 offset:64
	v_mov_b32_e32 v63, v125
	v_mov_b32_e32 v64, v126
	v_mad_u32_u24 v41, v41, s33, 0
	v_add_u32_e32 v43, 0xffffd300, v41
	v_add_u32_e32 v44, 0xffffd600, v41
	v_add_u32_e32 v45, 0xffffd900, v41
	v_add_u32_e32 v60, v43, v77
	s_waitcnt lgkmcnt(7)
	v_lshlrev_b32_e32 v34, 16, v34
	s_waitcnt lgkmcnt(6)
	v_lshlrev_b32_e32 v35, 16, v35
	v_add_u32_e32 v61, v44, v77
	v_add_u32_e32 v62, v45, v77
	ds_read_u16 v38, v60 offset:1536
	ds_read_u16 v39, v60 offset:1568
	ds_read_u16 v65, v61 offset:1536
	ds_read_u16 v68, v61 offset:1568
	ds_read_u16 v66, v62 offset:1536
	ds_read_u16 v69, v61 offset:1600
	ds_read_u16 v70, v60 offset:1600
	ds_read_u16 v51, v51 offset:1600
	s_waitcnt lgkmcnt(12)
	v_lshlrev_b32_e32 v37, 16, v37
	v_sub_f32_e32 v35, v35, v34
	v_sub_f32_e32 v60, v37, v34
	v_sub_f32_e32 v61, v34, v37
	s_waitcnt lgkmcnt(7)
	v_lshlrev_b32_e32 v38, 16, v38
	s_waitcnt lgkmcnt(5)
	v_lshlrev_b32_e32 v65, 16, v65
	v_sub_f32_e32 v67, v38, v37
	s_waitcnt lgkmcnt(3)
	v_lshlrev_b32_e32 v66, 16, v66
	v_sub_f32_e32 v71, v37, v38
	v_sub_f32_e32 v75, v65, v38
	v_add_u32_e32 v84, 0x300, v41
	v_add_u32_e32 v86, 0x600, v41
	v_add_u32_e32 v87, 0x900, v41
	v_lshlrev_b32_e32 v36, 16, v36
	v_readlane_b32 s0, v251, 32
	v_readlane_b32 s12, v251, 44
	v_readlane_b32 s13, v251, 45
	v_readlane_b32 s14, v251, 46
	v_readlane_b32 s15, v251, 47
	v_readlane_b32 s70, v251, 6
	v_readlane_b32 s71, v251, 7
	v_readlane_b32 s74, v251, 10
	v_readlane_b32 s75, v251, 11
	s_movk_i32 s0, 0x840
	s_movk_i32 s56, 0x210
	v_readlane_b32 s1, v251, 33
	v_readlane_b32 s2, v251, 34
	v_readlane_b32 s3, v251, 35
	v_readlane_b32 s4, v251, 36
	v_readlane_b32 s5, v251, 37
	v_readlane_b32 s6, v251, 38
	v_readlane_b32 s7, v251, 39
	v_readlane_b32 s8, v251, 40
	v_readlane_b32 s9, v251, 41
	v_readlane_b32 s10, v251, 42
	v_readlane_b32 s11, v251, 43
	v_readlane_b32 s65, v251, 1
	v_readlane_b32 s66, v251, 2
	v_readlane_b32 s67, v251, 3
	v_readlane_b32 s68, v251, 4
	v_readlane_b32 s69, v251, 5
	v_readlane_b32 s72, v251, 8
	v_readlane_b32 s73, v251, 9
	v_readlane_b32 s76, v251, 12
	v_readlane_b32 s77, v251, 13
	s_waitcnt vmcnt(8)
; __device__ __forceinline__ float bf2f(bf16_t v) { return __uint_as_float(((unsigned)v) << 16); }
; __device__ __forceinline__ void rwkv_prep_tile(const Params& p, int l, int tile, unsigned char* smem) {
;     ...
;   for (int nt = 0; nt < 4; ++nt) {
;     const int c = w * 64 + nt * 16 + fr;
;     const float m0k = mu0[256 + c], m1k = mu1[256 + c], kkc = p.rwkv_k_k[ld2 * 256 + c];
; #pragma unroll
;     for (int mt = 0; mt < 2; ++mt)
; #pragma unroll
;       for (int j = 0; j < 4; ++j) {
;         const int i = mt * 16 + fq * 4 + j;
;         const bf16_t* r0 = raw + (i + 1) * 384 + c;
;         const float u = bf2f(r0[0]), up = bf2f(r0[-384]), un = bf2f(r0[384]);
;         const float kq = (u + m0k * (up - u) + m1k * (un - u)) * kkc;
;         kkr[mt][nt][j] = kq;
;         ssq[mt][j] += kq * kq;
;       }
;   }
	v_fma_f32 v34, v46, v35, v34
	v_fma_f32 v35, v46, v61, v37
	s_waitcnt vmcnt(7)
	v_fmac_f32_e32 v34, v47, v60
	v_fmac_f32_e32 v35, v47, v67
	s_waitcnt vmcnt(6)
	v_mul_f32_e32 v114, v50, v34
	v_sub_f32_e32 v34, v38, v65
	v_fma_f32 v37, v46, v71, v38
	v_mul_f32_e32 v113, v50, v35
	v_sub_f32_e32 v35, v66, v65
	v_fmac_f32_e32 v65, v46, v34
	v_fmac_f32_e32 v37, v47, v75
	v_fmac_f32_e32 v65, v47, v35
	v_add_u32_e32 v34, v41, v77
	v_mul_f32_e32 v110, v50, v37
	v_mul_f32_e32 v107, v50, v65
	ds_read_u16 v35, v34 offset:768
	ds_read_u16 v37, v34
	ds_read_u16 v38, v34 offset:800
	ds_read_u16 v65, v34 offset:832
	ds_read_u16 v71, v34 offset:64
	s_waitcnt lgkmcnt(4)
	v_lshlrev_b32_e32 v35, 16, v35
	s_waitcnt lgkmcnt(3)
	v_lshlrev_b32_e32 v37, 16, v37
	ds_read_u16 v60, v34 offset:32
	ds_read_u16 v61, v62 offset:1568
	ds_read_u16 v62, v62 offset:1600
	v_add_u32_e32 v66, v84, v77
	v_add_u32_e32 v67, v86, v77
	ds_read_u16 v75, v34 offset:1536
	ds_read_u16 v76, v66 offset:1536
	ds_read_u16 v78, v66 offset:1568
	ds_read_u16 v79, v67 offset:1536
	ds_read_u16 v80, v67 offset:1568
	ds_read_u16 v81, v34 offset:1568
	ds_read_u16 v83, v66 offset:1600
	ds_read_u16 v82, v34 offset:1600
	s_waitcnt lgkmcnt(7)
	v_lshlrev_b32_e32 v34, 16, v75
	v_sub_f32_e32 v37, v37, v35
	v_fma_f32 v37, v46, v37, v35
	v_sub_f32_e32 v66, v34, v35
	v_fmac_f32_e32 v37, v47, v66
	v_mul_f32_e32 v112, v50, v37
	s_waitcnt lgkmcnt(6)
	v_lshlrev_b32_e32 v37, 16, v76
	v_sub_f32_e32 v35, v35, v34
	v_fma_f32 v35, v46, v35, v34
	v_sub_f32_e32 v66, v37, v34
	v_fmac_f32_e32 v35, v47, v66
	v_mul_f32_e32 v111, v50, v35
	s_waitcnt lgkmcnt(4)
	v_lshlrev_b32_e32 v35, 16, v79
	v_sub_f32_e32 v34, v34, v37
	v_fma_f32 v34, v46, v34, v37
	v_sub_f32_e32 v66, v35, v37
	v_fmac_f32_e32 v34, v47, v66
	v_add_u32_e32 v66, v87, v77
	ds_read_u16 v75, v66 offset:1536
	v_mul_f32_e32 v108, v50, v34
	ds_read_u16 v34, v66 offset:1568
	ds_read_u16 v76, v66 offset:1600
	ds_read_u16 v79, v67 offset:1600
	v_sub_f32_e32 v37, v37, v35
	s_waitcnt lgkmcnt(3)
	v_lshlrev_b32_e32 v66, 16, v75
	v_sub_f32_e32 v66, v66, v35
	v_fmac_f32_e32 v35, v46, v37
	v_fmac_f32_e32 v35, v47, v66
	v_mul_f32_e32 v109, v50, v35
	v_lshlrev_b32_e32 v35, 16, v56
	v_lshlrev_b32_e32 v37, 16, v57
	v_sub_f32_e32 v36, v36, v35
	s_waitcnt vmcnt(5)
	v_fma_f32 v36, v52, v36, v35
	v_sub_f32_e32 v46, v37, v35
	s_waitcnt vmcnt(4)
	v_fmac_f32_e32 v36, v53, v46
	s_waitcnt vmcnt(1)
	v_mul_f32_e32 v106, v63, v36
	v_lshlrev_b32_e32 v36, 16, v39
	v_sub_f32_e32 v35, v35, v37
	v_fma_f32 v35, v52, v35, v37
	v_sub_f32_e32 v39, v36, v37
	v_fmac_f32_e32 v35, v53, v39
	v_mul_f32_e32 v104, v63, v35
	v_lshlrev_b32_e32 v35, 16, v68
	v_sub_f32_e32 v37, v37, v36
	v_fma_f32 v37, v52, v37, v36
	v_sub_f32_e32 v39, v35, v36
	v_fmac_f32_e32 v37, v53, v39
	v_mul_f32_e32 v103, v63, v37
	v_lshlrev_b32_e32 v37, 16, v61
	v_sub_f32_e32 v36, v36, v35
	v_sub_f32_e32 v37, v37, v35
	v_fmac_f32_e32 v35, v52, v36
	v_fmac_f32_e32 v35, v53, v37
	v_mul_f32_e32 v101, v63, v35
	v_lshlrev_b32_e32 v35, 16, v38
	v_lshlrev_b32_e32 v36, 16, v60
	v_lshlrev_b32_e32 v37, 16, v81
	v_sub_f32_e32 v36, v36, v35
	v_fma_f32 v36, v52, v36, v35
	v_sub_f32_e32 v38, v37, v35
	v_fmac_f32_e32 v36, v53, v38
	v_mul_f32_e32 v99, v63, v36
	v_lshlrev_b32_e32 v36, 16, v78
	v_sub_f32_e32 v35, v35, v37
	v_fma_f32 v35, v52, v35, v37
	v_sub_f32_e32 v38, v36, v37
	v_fmac_f32_e32 v35, v53, v38
	v_mul_f32_e32 v98, v63, v35
	v_lshlrev_b32_e32 v35, 16, v80
	v_sub_f32_e32 v37, v37, v36
	v_fma_f32 v37, v52, v37, v36
	v_sub_f32_e32 v38, v35, v36
	s_waitcnt lgkmcnt(2)
	v_lshlrev_b32_e32 v34, 16, v34
	v_sub_f32_e32 v36, v36, v35
	v_sub_f32_e32 v34, v34, v35
	v_fmac_f32_e32 v35, v52, v36
	v_fmac_f32_e32 v35, v53, v34
	v_or_b32_e32 v34, 48, v72
	v_fmac_f32_e32 v37, v53, v38
	v_mul_f32_e32 v94, v63, v35
	v_lshlrev_b32_e32 v46, 16, v58
	v_ashrrev_i32_e32 v35, 31, v34
	v_add_u32_e32 v58, s42, v34
	v_mul_f32_e32 v96, v63, v37
	v_lshlrev_b32_e32 v47, 16, v59
	v_lshlrev_b64 v[36:37], 2, v[34:35]
	v_ashrrev_i32_e32 v59, 31, v58
	v_lshl_add_u64 v[38:39], s[52:53], 0, v[36:37]
	v_lshl_add_u64 v[36:37], s[54:55], 0, v[36:37]
	v_lshlrev_b64 v[56:57], 2, v[58:59]
	v_mov_b32_e32 v53, v127
	v_mov_b32_e32 v102, v128
	v_lshl_add_u64 v[36:37], s[78:79], 0, v[56:57]
	v_mov_b32_e32 v105, v129
	v_lshlrev_b32_e32 v35, 16, v51
	v_sub_f32_e32 v36, v47, v46
	v_fma_f32 v36, v55, v36, v46
	v_sub_f32_e32 v37, v35, v46
	v_fmac_f32_e32 v36, v54, v37
	s_waitcnt vmcnt(3)
	v_mul_f32_e32 v97, v64, v36
	v_lshlrev_b32_e32 v36, 16, v70
	v_sub_f32_e32 v37, v46, v35
	v_fma_f32 v37, v55, v37, v35
	v_sub_f32_e32 v38, v36, v35
	v_fmac_f32_e32 v37, v54, v38
	v_mul_f32_e32 v93, v64, v37
	v_lshlrev_b32_e32 v37, 16, v69
	v_sub_f32_e32 v35, v35, v36
	v_fma_f32 v35, v55, v35, v36
	v_sub_f32_e32 v38, v37, v36
	v_fmac_f32_e32 v35, v54, v38
	v_mul_f32_e32 v91, v64, v35
	v_lshlrev_b32_e32 v35, 16, v62
	v_sub_f32_e32 v36, v36, v37
	v_sub_f32_e32 v35, v35, v37
	v_fmac_f32_e32 v37, v55, v36
	v_fmac_f32_e32 v37, v54, v35
	v_lshlrev_b32_e32 v35, 16, v65
	v_lshlrev_b32_e32 v36, 16, v71
	v_mul_f32_e32 v89, v64, v37
	v_lshlrev_b32_e32 v37, 16, v82
	v_sub_f32_e32 v36, v36, v35
	v_fma_f32 v36, v55, v36, v35
	v_sub_f32_e32 v38, v37, v35
	v_fmac_f32_e32 v36, v54, v38
	v_mul_f32_e32 v82, v64, v36
	v_lshlrev_b32_e32 v36, 16, v83
	v_sub_f32_e32 v35, v35, v37
	v_fma_f32 v35, v55, v35, v37
	v_sub_f32_e32 v38, v36, v37
	v_fmac_f32_e32 v35, v54, v38
	v_mul_f32_e32 v80, v64, v35
	s_waitcnt lgkmcnt(0)
; __device__ __forceinline__ float bf2f(bf16_t v) { return __uint_as_float(((unsigned)v) << 16); }
; __device__ __forceinline__ float frcp(float x) { return __builtin_amdgcn_rcpf(x); }
; __device__ __forceinline__ void rwkv_prep_tile(const Params& p, int l, int tile, unsigned char* smem) {
;     ...
;         const int i = mt * 16 + fq * 4 + j;
;         const bf16_t* r0 = raw + (i + 1) * 384 + c;
;         const float u = bf2f(r0[0]), up = bf2f(r0[-384]), un = bf2f(r0[384]);
;         const float kq = (u + m0k * (up - u) + m1k * (un - u)) * kkc;
;         kkr[mt][nt][j] = kq;
;         ssq[mt][j] += kq * kq;
;       }
;   }
;   float inv[2][4];
; #pragma unroll
;   for (int mt = 0; mt < 2; ++mt)
; #pragma unroll
;     for (int j = 0; j < 4; ++j) {
;       const float tot = sum16(ssq[mt][j]);
;       inv[mt][j] = frcp(fmaxf(__builtin_amdgcn_sqrtf(tot), 1e-12f));
;     }
;   __syncthreads();
;   bf16_t* stg = (bf16_t*)smem;
; #pragma unroll
;   for (int nt = 0; nt < 4; ++nt) {
;     const int c = w * 64 + nt * 16 + fr;
;     const bf16_t* wup = p.WupT + ((size_t)(ld2 * 256 + c)) * 64 + fq * 8;
;     const bf16_t* aup = p.AupT + ((size_t)(ld2 * 256 + c)) * 64 + fq * 8;
;     const bf16x8 bw0 = *(const bf16x8*)wup, bw1 = *(const bf16x8*)(wup + 32);
;     const bf16x8 ba0 = *(const bf16x8*)aup, ba1 = *(const bf16x8*)(aup + 32);
;     const float w0c = p.rwkv_w0[ld2 * 256 + c], a0c = p.rwkv_a0[ld2 * 256 + c];
	v_lshlrev_b32_e32 v35, 16, v79
	v_sub_f32_e32 v37, v37, v36
	v_fma_f32 v37, v55, v37, v36
	v_sub_f32_e32 v38, v35, v36
	v_fmac_f32_e32 v37, v54, v38
	v_mul_f32_e32 v79, v64, v37
	v_lshlrev_b32_e32 v37, 16, v76
	v_sub_f32_e32 v36, v36, v35
	v_lshlrev_b32_e32 v75, 1, v34
	v_sub_f32_e32 v37, v37, v35
	v_fmac_f32_e32 v35, v55, v36
	v_add_u32_e32 v34, v42, v75
	v_add_u32_e32 v36, v43, v75
	v_add_u32_e32 v38, v44, v75
	v_add_u32_e32 v39, v45, v75
	v_add_u32_e32 v41, v41, v75
	ds_read_u16 v42, v34 offset:768
	ds_read_u16 v43, v34 offset:1536
	ds_read_u16 v36, v36 offset:1536
	ds_read_u16 v38, v38 offset:1536
	ds_read_u16 v39, v39 offset:1536
	ds_read_u16 v44, v41 offset:768
	ds_read_u16 v45, v41
	ds_read_u16 v34, v34
	v_fmac_f32_e32 v35, v54, v37
	v_mul_f32_e32 v85, v64, v35
	s_waitcnt lgkmcnt(7)
	v_lshlrev_b32_e32 v35, 16, v42
	s_waitcnt lgkmcnt(6)
	v_lshlrev_b32_e32 v37, 16, v43
	s_waitcnt lgkmcnt(0)
	v_lshlrev_b32_e32 v34, 16, v34
	v_sub_f32_e32 v34, v34, v35
	v_sub_f32_e32 v42, v37, v35
	v_lshlrev_b32_e32 v44, 16, v44
	v_or_b32_e32 v66, 16, v32
	v_or_b32_e32 v60, 32, v32
	v_lshl_add_u64 v[68:69], s[70:71], 0, v[48:49]
	v_lshl_add_u64 v[70:71], s[74:75], 0, v[48:49]
	v_mul_f32_e32 v50, v106, v106
	v_fmac_f32_e32 v50, v114, v114
	v_fmac_f32_e32 v50, v97, v97
	v_mul_f32_e32 v90, v104, v104
	v_fmac_f32_e32 v90, v113, v113
	v_mul_f32_e32 v92, v103, v103
	v_fmac_f32_e32 v92, v110, v110
	v_fmac_f32_e32 v90, v93, v93
	v_fmac_f32_e32 v92, v91, v91
	s_waitcnt vmcnt(2)
	v_fma_f32 v34, v53, v34, v35
	s_waitcnt vmcnt(1)
	v_fmac_f32_e32 v34, v102, v42
	v_sub_f32_e32 v35, v35, v37
	s_waitcnt vmcnt(0)
	v_mul_f32_e32 v83, v105, v34
	v_lshlrev_b32_e32 v34, 16, v36
	v_fma_f32 v35, v53, v35, v37
	v_sub_f32_e32 v36, v34, v37
	v_fmac_f32_e32 v35, v102, v36
	v_mul_f32_e32 v81, v105, v35
	v_lshlrev_b32_e32 v35, 16, v38
	v_sub_f32_e32 v36, v37, v34
	v_fma_f32 v36, v53, v36, v34
	v_sub_f32_e32 v37, v35, v34
	v_fmac_f32_e32 v36, v102, v37
	v_mul_f32_e32 v78, v105, v36
	v_lshlrev_b32_e32 v36, 16, v39
	v_sub_f32_e32 v34, v34, v35
	v_sub_f32_e32 v36, v36, v35
	v_fmac_f32_e32 v35, v53, v34
	v_fmac_f32_e32 v35, v102, v36
	v_mul_f32_e32 v76, v105, v35
	ds_read_u16 v35, v41 offset:1536
	v_lshlrev_b32_e32 v34, 16, v45
	v_mov_b32_e32 v41, v164
	v_add_u32_e32 v36, v84, v75
	v_add_u32_e32 v37, v86, v75
	v_add_u32_e32 v38, v87, v75
	s_waitcnt lgkmcnt(0)
	v_lshlrev_b32_e32 v55, 16, v35
	v_sub_f32_e32 v34, v34, v44
	v_lshl_add_u64 v[62:63], s[12:13], 0, v[40:41]
	v_lshlrev_b64 v[42:43], 7, v[32:33]
	ds_read_u16 v39, v36 offset:1536
	ds_read_u16 v51, v37 offset:1536
	ds_read_u16 v54, v38 offset:1536
	v_fma_f32 v38, v53, v34, v44
	v_sub_f32_e32 v34, v55, v44
	v_lshl_add_u64 v[36:37], v[62:63], 0, v[42:43]
	v_fmac_f32_e32 v38, v102, v34
	s_waitcnt lgkmcnt(0)
	s_barrier
	global_load_dwordx4 v[32:35], v[36:37], off
	v_mul_f32_e32 v88, v105, v38
	v_lshlrev_b32_e32 v84, 16, v39
	global_load_dwordx4 v[36:39], v[36:37], off offset:64
	v_lshl_add_u64 v[64:65], s[14:15], 0, v[40:41]
	v_sub_f32_e32 v46, v44, v55
	v_lshl_add_u64 v[44:45], v[64:65], 0, v[42:43]
	global_load_dwordx4 v[40:43], v[44:45], off
	global_load_dword v115, v[68:69], off
	v_fma_f32 v46, v53, v46, v55
	v_sub_f32_e32 v47, v84, v55
	v_fmac_f32_e32 v46, v102, v47
	v_mul_f32_e32 v87, v105, v46
	global_load_dwordx4 v[44:47], v[44:45], off offset:64
	v_lshlrev_b32_e32 v51, 16, v51
	global_load_dword v116, v[70:71], off
	v_sub_f32_e32 v55, v55, v84
	v_fma_f32 v55, v53, v55, v84
	v_sub_f32_e32 v48, v51, v84
	v_fmac_f32_e32 v50, v83, v83
	v_fmac_f32_e32 v55, v102, v48
	v_lshlrev_b32_e32 v48, 16, v54
	v_sub_f32_e32 v49, v84, v51
	v_sub_f32_e32 v48, v48, v51
	v_fmac_f32_e32 v51, v53, v49
	v_add_f32_dpp v49, v50, v50 quad_perm:[1,0,3,2] row_mask:0xf bank_mask:0xf bound_ctrl:1
	v_fmac_f32_e32 v90, v81, v81
	v_fmac_f32_e32 v92, v78, v78
	v_add_f32_dpp v49, v49, v49 quad_perm:[2,3,0,1] row_mask:0xf bank_mask:0xf bound_ctrl:1
	v_fmac_f32_e32 v51, v102, v48
	v_add_f32_dpp v50, v92, v92 quad_perm:[1,0,3,2] row_mask:0xf bank_mask:0xf bound_ctrl:1
	v_add_f32_dpp v49, v49, v49 row_half_mirror row_mask:0xf bank_mask:0xf bound_ctrl:1
	v_mul_f32_e32 v95, v101, v101
	v_add_f32_dpp v50, v50, v50 quad_perm:[2,3,0,1] row_mask:0xf bank_mask:0xf bound_ctrl:1
	v_add_f32_dpp v49, v49, v49 row_mirror row_mask:0xf bank_mask:0xf bound_ctrl:1
	v_sqrt_f32_e32 v49, v49
	v_add_f32_dpp v50, v50, v50 row_half_mirror row_mask:0xf bank_mask:0xf bound_ctrl:1
	v_fmac_f32_e32 v95, v107, v107
	v_mul_f32_e32 v100, v99, v99
	v_max_f32_e32 v48, 0x2b8cbccc, v49
	v_add_f32_dpp v49, v90, v90 quad_perm:[1,0,3,2] row_mask:0xf bank_mask:0xf bound_ctrl:1
	v_add_f32_dpp v50, v50, v50 row_mirror row_mask:0xf bank_mask:0xf bound_ctrl:1
	v_sqrt_f32_e32 v50, v50
	v_add_f32_dpp v49, v49, v49 quad_perm:[2,3,0,1] row_mask:0xf bank_mask:0xf bound_ctrl:1
	v_fmac_f32_e32 v100, v112, v112
	v_fmac_f32_e32 v95, v89, v89
	v_add_f32_dpp v49, v49, v49 row_half_mirror row_mask:0xf bank_mask:0xf bound_ctrl:1
	v_fmac_f32_e32 v100, v82, v82
	v_fmac_f32_e32 v95, v76, v76
	v_add_f32_dpp v49, v49, v49 row_mirror row_mask:0xf bank_mask:0xf bound_ctrl:1
	v_sqrt_f32_e32 v49, v49
	v_fmac_f32_e32 v100, v88, v88
	v_mul_f32_e32 v86, v105, v55
	v_mul_f32_e32 v84, v105, v51
	v_rcp_f32_e32 v105, v48
	v_max_f32_e32 v48, 0x2b8cbccc, v49
	v_add_f32_dpp v49, v95, v95 quad_perm:[1,0,3,2] row_mask:0xf bank_mask:0xf bound_ctrl:1
	v_rcp_f32_e32 v102, v48
	v_max_f32_e32 v48, 0x2b8cbccc, v50
	v_add_f32_dpp v49, v49, v49 quad_perm:[2,3,0,1] row_mask:0xf bank_mask:0xf bound_ctrl:1
	v_add_f32_dpp v50, v100, v100 quad_perm:[1,0,3,2] row_mask:0xf bank_mask:0xf bound_ctrl:1
	v_mul_f32_e32 v117, v98, v98
; __device__ __forceinline__ bf16_t f2bf(float f) { return (bf16_t)(pack2(f, 0.f) & 0xffffu); }
; __device__ __forceinline__ float frcp(float x) { return __builtin_amdgcn_rcpf(x); }
; __device__ __forceinline__ float sigmoidf_(float x) { return frcp(1.f + __expf(-x)); }
; #define MFMA(a, b, c) __builtin_amdgcn_mfma_f32_16x16x32_bf16(a, b, c, 0, 0, 0)
; __device__ __forceinline__ void rwkv_prep_tile(const Params& p, int l, int tile, unsigned char* smem) {
;     ...
;   float inv[2][4];
; #pragma unroll
;   for (int mt = 0; mt < 2; ++mt)
; #pragma unroll
;     for (int j = 0; j < 4; ++j) {
;       const float tot = sum16(ssq[mt][j]);
;       inv[mt][j] = frcp(fmaxf(__builtin_amdgcn_sqrtf(tot), 1e-12f));
;     }
;   __syncthreads();
;   bf16_t* stg = (bf16_t*)smem;
; #pragma unroll
;   for (int nt = 0; nt < 4; ++nt) {
;     const int c = w * 64 + nt * 16 + fr;
;     const bf16_t* wup = p.WupT + ((size_t)(ld2 * 256 + c)) * 64 + fq * 8;
;     const bf16_t* aup = p.AupT + ((size_t)(ld2 * 256 + c)) * 64 + fq * 8;
;     const bf16x8 bw0 = *(const bf16x8*)wup, bw1 = *(const bf16x8*)(wup + 32);
;     const bf16x8 ba0 = *(const bf16x8*)aup, ba1 = *(const bf16x8*)(aup + 32);
;     const float w0c = p.rwkv_w0[ld2 * 256 + c], a0c = p.rwkv_a0[ld2 * 256 + c];
; #pragma unroll
;     for (int mt = 0; mt < 2; ++mt) {
;       f32x4 accw = (f32x4){0.f, 0.f, 0.f, 0.f}, acca = (f32x4){0.f, 0.f, 0.f, 0.f};
;       accw = MFMA(aw[mt][0], bw0, accw);
;       accw = MFMA(aw[mt][1], bw1, accw);
;       acca = MFMA(aa[mt][0], ba0, acca);
;       acca = MFMA(aa[mt][1], ba1, acca);
; #pragma unroll
;       for (int j = 0; j < 4; ++j) {
;         const int i = mt * 16 + fq * 4 + j;
;         const float ew = 0.6065306597f * sigmoidf_(w0c + accw[j]);
;         const float a = sigmoidf_(a0c + acca[j]);
;         const float kk = kkr[mt][nt][j] * inv[mt][j];
;         bf16_t* o = stg + i * 264 + c;
;         o[0] = f2bf(ew);
;         o[32 * 264] = f2bf(a);
;         o[2 * 32 * 264] = f2bf(kk);
;       }
;     }
	v_add_f32_dpp v49, v49, v49 row_half_mirror row_mask:0xf bank_mask:0xf bound_ctrl:1
	v_add_f32_dpp v50, v50, v50 quad_perm:[2,3,0,1] row_mask:0xf bank_mask:0xf bound_ctrl:1
	v_fmac_f32_e32 v117, v111, v111
	v_add_f32_dpp v49, v49, v49 row_mirror row_mask:0xf bank_mask:0xf bound_ctrl:1
	v_add_f32_dpp v50, v50, v50 row_half_mirror row_mask:0xf bank_mask:0xf bound_ctrl:1
	v_sqrt_f32_e32 v49, v49
	v_fmac_f32_e32 v117, v80, v80
	v_add_f32_dpp v50, v50, v50 row_mirror row_mask:0xf bank_mask:0xf bound_ctrl:1
	v_sqrt_f32_e32 v50, v50
	v_rcp_f32_e32 v100, v48
	v_max_f32_e32 v48, 0x2b8cbccc, v49
	v_fmac_f32_e32 v117, v87, v87
	v_rcp_f32_e32 v95, v48
	v_max_f32_e32 v48, 0x2b8cbccc, v50
	v_rcp_f32_e32 v92, v48
	v_mul_f32_e32 v118, v96, v96
	v_add_f32_dpp v48, v117, v117 quad_perm:[1,0,3,2] row_mask:0xf bank_mask:0xf bound_ctrl:1
	v_fmac_f32_e32 v118, v108, v108
	v_fmac_f32_e32 v118, v79, v79
	v_add_f32_dpp v48, v48, v48 quad_perm:[2,3,0,1] row_mask:0xf bank_mask:0xf bound_ctrl:1
	v_fmac_f32_e32 v118, v86, v86
	v_mul_f32_e32 v52, v94, v94
	v_add_f32_dpp v48, v48, v48 row_half_mirror row_mask:0xf bank_mask:0xf bound_ctrl:1
	v_add_f32_dpp v49, v118, v118 quad_perm:[1,0,3,2] row_mask:0xf bank_mask:0xf bound_ctrl:1
	v_fmac_f32_e32 v52, v109, v109
	v_add_f32_dpp v48, v48, v48 row_mirror row_mask:0xf bank_mask:0xf bound_ctrl:1
	v_sqrt_f32_e32 v48, v48
	v_add_f32_dpp v49, v49, v49 quad_perm:[2,3,0,1] row_mask:0xf bank_mask:0xf bound_ctrl:1
	v_fmac_f32_e32 v52, v85, v85
	v_fmac_f32_e32 v52, v84, v84
	v_add_f32_dpp v49, v49, v49 row_half_mirror row_mask:0xf bank_mask:0xf bound_ctrl:1
	v_max_f32_e32 v48, 0x2b8cbccc, v48
	v_rcp_f32_e32 v90, v48
	v_add_f32_dpp v49, v49, v49 row_mirror row_mask:0xf bank_mask:0xf bound_ctrl:1
	v_sqrt_f32_e32 v53, v49
	s_waitcnt vmcnt(5)
	v_mfma_f32_16x16x32_bf16 v[48:51], v[28:31], v[32:35], 0
	v_add_f32_dpp v52, v52, v52 quad_perm:[1,0,3,2] row_mask:0xf bank_mask:0xf bound_ctrl:1
	global_load_dword v130, v[68:69], off offset:64
	s_nop 0
	global_load_dword v69, v[68:69], off offset:128
	v_add_f32_dpp v52, v52, v52 quad_perm:[2,3,0,1] row_mask:0xf bank_mask:0xf bound_ctrl:1
	s_waitcnt vmcnt(6)
	v_mfma_f32_16x16x32_bf16 v[48:51], v[24:27], v[36:39], v[48:51]
	v_max_f32_e32 v117, 0x2b8cbccc, v53
	v_add_f32_dpp v52, v52, v52 row_half_mirror row_mask:0xf bank_mask:0xf bound_ctrl:1
	v_rcp_f32_e32 v68, v117
	v_mfma_f32_16x16x32_bf16 v[32:35], v[12:15], v[32:35], 0
	v_add_f32_dpp v52, v52, v52 row_mirror row_mask:0xf bank_mask:0xf bound_ctrl:1
	v_sqrt_f32_e32 v118, v52
	s_waitcnt vmcnt(4)
	s_nop 0
	v_add_f32_e32 v48, v115, v48
	v_mfma_f32_16x16x32_bf16 v[52:55], v[20:23], v[40:43], 0
	v_mul_f32_e32 v48, 0xbfb8aa3b, v48
	v_exp_f32_e32 v48, v48
	v_max_f32_e32 v117, 0x2b8cbccc, v118
	s_waitcnt vmcnt(3)
	v_mfma_f32_16x16x32_bf16 v[118:121], v[16:19], v[44:47], v[52:55]
	global_load_dword v131, v[70:71], off offset:64
	s_nop 1
	global_load_dword v52, v[70:71], off offset:128
	v_add_f32_e32 v48, 1.0, v48
	v_rcp_f32_e32 v53, v48
	s_waitcnt vmcnt(4)
	s_nop 0
	v_add_f32_e32 v48, v116, v118
	v_mul_f32_e32 v48, 0xbfb8aa3b, v48
	v_exp_f32_e32 v54, v48
	v_add_u32_e32 v70, 0, v77
	v_mul_f32_e32 v53, 0x3f1b4598, v53
	v_mad_u32_u24 v71, v73, s0, v70
	v_add_f32_e32 v54, 1.0, v54
	v_rcp_f32_e32 v54, v54
	v_cvt_pk_bf16_f32 v53, v53, s0
	v_add_f32_e32 v49, v115, v49
	v_mul_f32_e32 v49, 0xbfb8aa3b, v49
	ds_write_b16 v71, v53
	v_cvt_pk_bf16_f32 v53, v54, s0
	v_exp_f32_e32 v49, v49
	ds_write_b16 v71, v53 offset:16896
	v_add_f32_e32 v53, v116, v119
	v_mul_f32_e32 v53, 0xbfb8aa3b, v53
	v_exp_f32_e32 v53, v53
	v_add_f32_e32 v49, 1.0, v49
	v_rcp_f32_e32 v49, v49
	v_add_f32_e32 v50, v115, v50
	v_add_f32_e32 v53, 1.0, v53
	v_rcp_f32_e32 v53, v53
	v_mul_f32_e32 v50, 0xbfb8aa3b, v50
	v_exp_f32_e32 v50, v50
	v_mul_f32_e32 v55, v114, v105
	v_mul_f32_e32 v49, 0x3f1b4598, v49
	v_cvt_pk_bf16_f32 v54, v55, s0
	v_mad_u32_u24 v77, v74, s56, v70
	v_cvt_pk_bf16_f32 v49, v49, s0
	ds_write_b16 v71, v54 offset:33792
	ds_write_b16 v77, v49
	v_cvt_pk_bf16_f32 v49, v53, s0
	ds_write_b16 v77, v49 offset:16896
	v_add_f32_e32 v49, 1.0, v50
	v_add_f32_e32 v50, v116, v120
	v_mul_f32_e32 v50, 0xbfb8aa3b, v50
	v_exp_f32_e32 v50, v50
	v_mul_f32_e32 v54, v113, v102
	v_rcp_f32_e32 v49, v49
	v_cvt_pk_bf16_f32 v53, v54, s0
	v_add_f32_e32 v50, 1.0, v50
	ds_write_b16 v77, v53 offset:33792
	v_rcp_f32_e32 v53, v50
	v_mul_f32_e32 v49, 0x3f1b4598, v49
	v_mad_u32_u24 v50, v74, s56, s56
	v_ashrrev_i32_e32 v67, 31, v66
	v_mul_f32_e32 v54, v110, v100
	v_add_u32_e32 v132, v70, v50
	v_cvt_pk_bf16_f32 v49, v49, s0
	v_mfma_f32_16x16x32_bf16 v[40:43], v[4:7], v[40:43], 0
	v_add_f32_e32 v51, v115, v51
	ds_write_b16 v132, v49
	v_cvt_pk_bf16_f32 v49, v53, s0
	v_cvt_pk_bf16_f32 v53, v54, s0
	v_lshlrev_b64 v[54:55], 7, v[66:67]
	v_mul_f32_e32 v51, 0xbfb8aa3b, v51
	v_lshl_add_u64 v[66:67], v[62:63], 0, v[54:55]
	v_exp_f32_e32 v51, v51
	v_mfma_f32_16x16x32_bf16 v[32:35], v[8:11], v[36:39], v[32:35]
	global_load_dwordx4 v[36:39], v[66:67], off
	ds_write_b16 v132, v49 offset:16896
	v_add_f32_e32 v49, 1.0, v51
	v_mfma_f32_16x16x32_bf16 v[44:47], v[0:3], v[44:47], v[40:43]
	v_add_f32_e32 v51, v116, v121
	global_load_dwordx4 v[118:121], v[66:67], off offset:64
	s_nop 1
	v_add_f32_e32 v32, v115, v32
	v_lshl_add_u64 v[40:41], v[64:65], 0, v[54:55]
	global_load_dwordx4 v[122:125], v[40:41], off
	global_load_dwordx4 v[126:129], v[40:41], off offset:64
	v_mul_f32_e32 v51, 0xbfb8aa3b, v51
	v_mul_f32_e32 v32, 0xbfb8aa3b, v32
	v_rcp_f32_e32 v49, v49
	v_exp_f32_e32 v51, v51
	v_exp_f32_e32 v32, v32
	v_add_f32_e32 v42, v116, v44
	v_mul_f32_e32 v42, 0xbfb8aa3b, v42
	v_exp_f32_e32 v40, v42
	ds_write_b16 v132, v53 offset:33792
; __device__ __forceinline__ bf16_t f2bf(float f) { return (bf16_t)(pack2(f, 0.f) & 0xffffu); }
; __device__ __forceinline__ float sigmoidf_(float x) { return frcp(1.f + __expf(-x)); }
; #define MFMA(a, b, c) __builtin_amdgcn_mfma_f32_16x16x32_bf16(a, b, c, 0, 0, 0)
; __device__ __forceinline__ void rwkv_prep_tile(const Params& p, int l, int tile, unsigned char* smem) {
;     ...
; #pragma unroll
;     for (int mt = 0; mt < 2; ++mt) {
;       f32x4 accw = (f32x4){0.f, 0.f, 0.f, 0.f}, acca = (f32x4){0.f, 0.f, 0.f, 0.f};
;       accw = MFMA(aw[mt][0], bw0, accw);
;       accw = MFMA(aw[mt][1], bw1, accw);
;       acca = MFMA(aa[mt][0], ba0, acca);
;       acca = MFMA(aa[mt][1], ba1, acca);
; #pragma unroll
;       for (int j = 0; j < 4; ++j) {
;         const int i = mt * 16 + fq * 4 + j;
;         const float ew = 0.6065306597f * sigmoidf_(w0c + accw[j]);
;         const float a = sigmoidf_(a0c + acca[j]);
;         const float kk = kkr[mt][nt][j] * inv[mt][j];
;         bf16_t* o = stg + i * 264 + c;
;         o[0] = f2bf(ew);
;         o[32 * 264] = f2bf(a);
;         o[2 * 32 * 264] = f2bf(kk);
;       }
;     }
	v_mul_f32_e32 v53, 0x3f1b4598, v49
	v_add_f32_e32 v49, 1.0, v51
	v_add_f32_e32 v32, 1.0, v32
	v_rcp_f32_e32 v51, v49
	v_rcp_f32_e32 v32, v32
	v_add_f32_e32 v40, 1.0, v40
	v_add_f32_e32 v33, v115, v33
	v_rcp_f32_e32 v40, v40
	v_mul_f32_e32 v33, 0xbfb8aa3b, v33
	v_mad_u32_u24 v49, v74, s56, v209
	v_exp_f32_e32 v33, v33
	v_add_u32_e32 v133, v70, v49
	v_cvt_pk_bf16_f32 v51, v51, s0
	v_mul_f32_e32 v32, 0x3f1b4598, v32
	v_mad_u32_u24 v43, v74, s56, v210
	ds_write_b16 v133, v51 offset:16896
	v_add_u32_e32 v51, v70, v43
	v_cvt_pk_bf16_f32 v32, v32, s0
	ds_write_b16 v51, v32
	v_cvt_pk_bf16_f32 v32, v40, s0
	ds_write_b16 v51, v32 offset:16896
	v_add_f32_e32 v32, 1.0, v33
	v_add_f32_e32 v33, v116, v45
	v_mul_f32_e32 v33, 0xbfb8aa3b, v33
	v_exp_f32_e32 v33, v33
	v_rcp_f32_e32 v32, v32
	v_cvt_pk_bf16_f32 v53, v53, s0
	v_mad_u32_u24 v42, v74, s56, v211
	v_add_f32_e32 v33, 1.0, v33
	v_rcp_f32_e32 v33, v33
	v_mul_f32_e32 v32, 0x3f1b4598, v32
	v_add_f32_e32 v34, v115, v34
	ds_write_b16 v133, v53
	v_add_u32_e32 v53, v70, v42
	v_cvt_pk_bf16_f32 v32, v32, s0
	v_mul_f32_e32 v34, 0xbfb8aa3b, v34
	v_exp_f32_e32 v34, v34
	ds_write_b16 v53, v32
	v_cvt_pk_bf16_f32 v32, v33, s0
	v_add_f32_e32 v33, v116, v46
	v_mul_f32_e32 v33, 0xbfb8aa3b, v33
	v_exp_f32_e32 v33, v33
	ds_write_b16 v53, v32 offset:16896
	v_add_f32_e32 v32, 1.0, v34
	v_rcp_f32_e32 v32, v32
	v_mul_f32_e32 v107, v107, v95
	v_add_f32_e32 v33, 1.0, v33
	v_add_f32_e32 v35, v115, v35
	v_cvt_pk_bf16_f32 v41, v107, s0
	v_rcp_f32_e32 v33, v33
	v_mul_f32_e32 v35, 0xbfb8aa3b, v35
	ds_write_b16 v133, v41 offset:33792
	v_mul_f32_e32 v41, v112, v92
	v_exp_f32_e32 v35, v35
	v_cvt_pk_bf16_f32 v40, v41, s0
	v_mul_f32_e32 v32, 0x3f1b4598, v32
	v_mad_u32_u24 v41, v74, s56, v212
	v_add_u32_e32 v134, v70, v41
	v_cvt_pk_bf16_f32 v32, v32, s0
	ds_write_b16 v134, v32
	v_cvt_pk_bf16_f32 v32, v33, s0
	v_add_f32_e32 v33, v116, v47
	ds_write_b16 v134, v32 offset:16896
	v_add_f32_e32 v32, 1.0, v35
	v_mul_f32_e32 v33, 0xbfb8aa3b, v33
	v_rcp_f32_e32 v32, v32
	v_exp_f32_e32 v33, v33
	ds_write_b16 v51, v40 offset:33792
	v_mul_f32_e32 v40, v111, v90
	v_cvt_pk_bf16_f32 v34, v40, s0
	v_mul_f32_e32 v44, 0x3f1b4598, v32
	v_add_f32_e32 v32, 1.0, v33
	ds_write_b16 v53, v34 offset:33792
	v_mul_f32_e32 v34, v108, v68
	v_rcp_f32_e32 v45, v32
	v_cvt_pk_bf16_f32 v34, v34, s0
	ds_write_b16 v134, v34 offset:33792
	s_waitcnt vmcnt(3)
	v_mfma_f32_16x16x32_bf16 v[32:35], v[28:31], v[36:39], 0
	v_mad_u32_u24 v40, v74, s56, v213
	v_add_u32_e32 v70, v70, v40
	v_cvt_pk_bf16_f32 v44, v44, s0
	ds_write_b16 v70, v44
	v_cvt_pk_bf16_f32 v55, v45, s0
	s_waitcnt vmcnt(1)
	v_mfma_f32_16x16x32_bf16 v[44:47], v[20:23], v[122:125], 0
	v_rcp_f32_e32 v48, v117
	ds_write_b16 v70, v55 offset:16896
	v_ashrrev_i32_e32 v61, 31, v60
	v_mfma_f32_16x16x32_bf16 v[32:35], v[24:27], v[118:121], v[32:35]
	v_mul_f32_e32 v54, v109, v48
	v_cvt_pk_bf16_f32 v54, v54, s0
	ds_write_b16 v70, v54 offset:33792
	s_waitcnt vmcnt(0)
	v_mfma_f32_16x16x32_bf16 v[44:47], v[16:19], v[126:129], v[44:47]
	v_mul_f32_e32 v54, v106, v105
	s_nop 1
	v_add_f32_e32 v32, v130, v32
	v_mul_f32_e32 v32, 0xbfb8aa3b, v32
	v_exp_f32_e32 v32, v32
	v_add_f32_e32 v33, v130, v33
	s_nop 0
	v_add_f32_e32 v44, v131, v44
	v_mul_f32_e32 v44, 0xbfb8aa3b, v44
	v_exp_f32_e32 v44, v44
	v_add_f32_e32 v32, 1.0, v32
	v_rcp_f32_e32 v32, v32
	v_mul_f32_e32 v33, 0xbfb8aa3b, v33
	v_add_f32_e32 v44, 1.0, v44
	v_rcp_f32_e32 v44, v44
	v_exp_f32_e32 v33, v33
	v_mul_f32_e32 v32, 0x3f1b4598, v32
	v_cvt_pk_bf16_f32 v32, v32, s0
	ds_write_b16 v71, v32 offset:32
	v_cvt_pk_bf16_f32 v32, v44, s0
	ds_write_b16 v71, v32 offset:16928
	v_add_f32_e32 v32, 1.0, v33
	v_add_f32_e32 v33, v131, v45
	v_mul_f32_e32 v33, 0xbfb8aa3b, v33
	v_exp_f32_e32 v33, v33
	v_rcp_f32_e32 v32, v32
	v_add_f32_e32 v34, v130, v34
	v_cvt_pk_bf16_f32 v44, v54, s0
	v_add_f32_e32 v33, 1.0, v33
	v_rcp_f32_e32 v33, v33
	v_mul_f32_e32 v32, 0x3f1b4598, v32
	v_cvt_pk_bf16_f32 v32, v32, s0
	v_mul_f32_e32 v34, 0xbfb8aa3b, v34
	ds_write_b16 v71, v44 offset:33824
	v_exp_f32_e32 v34, v34
	ds_write_b16 v77, v32 offset:32
	v_cvt_pk_bf16_f32 v32, v33, s0
	v_add_f32_e32 v33, v131, v46
	v_mul_f32_e32 v33, 0xbfb8aa3b, v33
	v_exp_f32_e32 v33, v33
	ds_write_b16 v77, v32 offset:16928
	v_add_f32_e32 v32, 1.0, v34
	v_rcp_f32_e32 v32, v32
	v_add_f32_e32 v33, 1.0, v33
	v_add_f32_e32 v35, v130, v35
	v_rcp_f32_e32 v33, v33
	v_mul_f32_e32 v35, 0xbfb8aa3b, v35
	v_exp_f32_e32 v35, v35
	v_mul_f32_e32 v32, 0x3f1b4598, v32
	v_cvt_pk_bf16_f32 v32, v32, s0
	ds_write_b16 v132, v32 offset:32
	v_cvt_pk_bf16_f32 v32, v33, s0
	v_add_f32_e32 v33, v131, v47
	ds_write_b16 v132, v32 offset:16928
	v_add_f32_e32 v32, 1.0, v35
	v_mul_f32_e32 v33, 0xbfb8aa3b, v33
	v_rcp_f32_e32 v32, v32
	v_exp_f32_e32 v33, v33
	v_mul_f32_e32 v44, v104, v102
	v_cvt_pk_bf16_f32 v34, v44, s0
	v_lshlrev_b64 v[54:55], 7, v[60:61]
	ds_write_b16 v77, v34 offset:33824
	v_mul_f32_e32 v34, v103, v100
	v_lshl_add_u64 v[60:61], v[62:63], 0, v[54:55]
	v_cvt_pk_bf16_f32 v34, v34, s0
	v_mul_f32_e32 v66, 0x3f1b4598, v32
	v_add_f32_e32 v32, 1.0, v33
	global_load_dwordx4 v[44:47], v[60:61], off
	global_load_dwordx4 v[106:109], v[60:61], off offset:64
	ds_write_b16 v132, v34 offset:33824
	v_rcp_f32_e32 v67, v32
	v_mfma_f32_16x16x32_bf16 v[32:35], v[12:15], v[36:39], 0
	v_cvt_pk_bf16_f32 v36, v66, s0
	ds_write_b16 v133, v36 offset:32
	v_mul_f32_e32 v101, v101, v95
	v_mfma_f32_16x16x32_bf16 v[110:113], v[8:11], v[118:121], v[32:35]
	v_cvt_pk_bf16_f32 v60, v101, s0
	ds_write_b16 v133, v60 offset:33824
	v_mul_f32_e32 v60, v99, v92
	s_nop 0
	v_lshl_add_u64 v[32:33], v[64:65], 0, v[54:55]
	global_load_dwordx4 v[36:39], v[32:33], off
	s_nop 1
; __device__ __forceinline__ bf16_t f2bf(float f) { return (bf16_t)(pack2(f, 0.f) & 0xffffu); }
; __device__ __forceinline__ float sigmoidf_(float x) { return frcp(1.f + __expf(-x)); }
; #define MFMA(a, b, c) __builtin_amdgcn_mfma_f32_16x16x32_bf16(a, b, c, 0, 0, 0)
; __device__ __forceinline__ void rwkv_prep_tile(const Params& p, int l, int tile, unsigned char* smem) {
;     ...
;   for (int nt = 0; nt < 4; ++nt) {
;     const int c = w * 64 + nt * 16 + fr;
;     const bf16_t* wup = p.WupT + ((size_t)(ld2 * 256 + c)) * 64 + fq * 8;
;     const bf16_t* aup = p.AupT + ((size_t)(ld2 * 256 + c)) * 64 + fq * 8;
;     const bf16x8 bw0 = *(const bf16x8*)wup, bw1 = *(const bf16x8*)(wup + 32);
;     const bf16x8 ba0 = *(const bf16x8*)aup, ba1 = *(const bf16x8*)(aup + 32);
;     const float w0c = p.rwkv_w0[ld2 * 256 + c], a0c = p.rwkv_a0[ld2 * 256 + c];
; #pragma unroll
;     for (int mt = 0; mt < 2; ++mt) {
;       f32x4 accw = (f32x4){0.f, 0.f, 0.f, 0.f}, acca = (f32x4){0.f, 0.f, 0.f, 0.f};
;       accw = MFMA(aw[mt][0], bw0, accw);
;       accw = MFMA(aw[mt][1], bw1, accw);
;       acca = MFMA(aa[mt][0], ba0, acca);
;       acca = MFMA(aa[mt][1], ba1, acca);
; #pragma unroll
;       for (int j = 0; j < 4; ++j) {
;         const int i = mt * 16 + fq * 4 + j;
;         const float ew = 0.6065306597f * sigmoidf_(w0c + accw[j]);
;         const float a = sigmoidf_(a0c + acca[j]);
;         const float kk = kkr[mt][nt][j] * inv[mt][j];
;         bf16_t* o = stg + i * 264 + c;
;         o[0] = f2bf(ew);
;         o[32 * 264] = f2bf(a);
;         o[2 * 32 * 264] = f2bf(kk);
;       }
;     }
;   }
	v_add_f32_e32 v34, v130, v110
	v_mul_f32_e32 v55, 0xbfb8aa3b, v34
	global_load_dwordx4 v[32:35], v[32:33], off offset:64
	v_mfma_f32_16x16x32_bf16 v[114:117], v[4:7], v[122:125], 0
	v_exp_f32_e32 v55, v55
	v_cvt_pk_bf16_f32 v54, v67, s0
	ds_write_b16 v133, v54 offset:16928
	v_mfma_f32_16x16x32_bf16 v[114:117], v[0:3], v[126:129], v[114:117]
	v_add_f32_e32 v54, 1.0, v55
	v_rcp_f32_e32 v54, v54
	v_add_f32_e32 v61, v130, v111
	v_mul_f32_e32 v61, 0xbfb8aa3b, v61
	v_exp_f32_e32 v61, v61
	s_nop 2
	v_add_f32_e32 v55, v131, v114
	v_mul_f32_e32 v55, 0xbfb8aa3b, v55
	v_exp_f32_e32 v55, v55
	v_mul_f32_e32 v54, 0x3f1b4598, v54
	v_cvt_pk_bf16_f32 v54, v54, s0
	ds_write_b16 v51, v54 offset:32
	v_add_f32_e32 v55, 1.0, v55
	v_rcp_f32_e32 v55, v55
	v_cvt_pk_bf16_f32 v60, v60, s0
	ds_write_b16 v51, v60 offset:33824
	v_mul_f32_e32 v60, v98, v90
	v_cvt_pk_bf16_f32 v54, v55, s0
	v_add_f32_e32 v55, v131, v115
	v_mul_f32_e32 v55, 0xbfb8aa3b, v55
	v_exp_f32_e32 v55, v55
	ds_write_b16 v51, v54 offset:16928
	v_add_f32_e32 v54, 1.0, v61
	v_rcp_f32_e32 v54, v54
	v_add_f32_e32 v55, 1.0, v55
	v_rcp_f32_e32 v55, v55
	v_add_f32_e32 v61, v130, v112
	v_mul_f32_e32 v54, 0x3f1b4598, v54
	v_mul_f32_e32 v61, 0xbfb8aa3b, v61
	v_cvt_pk_bf16_f32 v54, v54, s0
	v_exp_f32_e32 v61, v61
	ds_write_b16 v53, v54 offset:32
	v_cvt_pk_bf16_f32 v54, v55, s0
	v_add_f32_e32 v55, v131, v116
	v_mul_f32_e32 v55, 0xbfb8aa3b, v55
	v_exp_f32_e32 v55, v55
	ds_write_b16 v53, v54 offset:16928
	v_add_f32_e32 v54, 1.0, v61
	v_rcp_f32_e32 v54, v54
	v_add_f32_e32 v55, 1.0, v55
	v_rcp_f32_e32 v55, v55
	v_cvt_pk_bf16_f32 v60, v60, s0
	v_mul_f32_e32 v54, 0x3f1b4598, v54
	v_cvt_pk_bf16_f32 v54, v54, s0
	ds_write_b16 v134, v54 offset:32
	v_add_f32_e32 v54, v130, v113
	ds_write_b16 v53, v60 offset:33824
	v_mul_f32_e32 v60, v96, v68
	v_mul_f32_e32 v54, 0xbfb8aa3b, v54
	v_cvt_pk_bf16_f32 v55, v55, s0
	v_exp_f32_e32 v54, v54
	ds_write_b16 v134, v55 offset:16928
	v_cvt_pk_bf16_f32 v55, v60, s0
	v_add_f32_e32 v60, v131, v117
	v_mul_f32_e32 v60, 0xbfb8aa3b, v60
	v_exp_f32_e32 v60, v60
	s_waitcnt vmcnt(3)
	v_mfma_f32_16x16x32_bf16 v[110:113], v[28:31], v[44:47], 0
	v_add_f32_e32 v54, 1.0, v54
	v_rcp_f32_e32 v54, v54
	ds_write_b16 v134, v55 offset:33824
	v_add_f32_e32 v55, 1.0, v60
	v_rcp_f32_e32 v55, v55
	s_waitcnt vmcnt(2)
	v_mfma_f32_16x16x32_bf16 v[110:113], v[24:27], v[106:109], v[110:113]
	v_mul_f32_e32 v54, 0x3f1b4598, v54
	v_cvt_pk_bf16_f32 v54, v54, s0
	ds_write_b16 v70, v54 offset:32
	s_waitcnt vmcnt(1)
	v_mfma_f32_16x16x32_bf16 v[114:117], v[20:23], v[36:39], 0
	v_cvt_pk_bf16_f32 v54, v55, s0
	s_nop 1
	v_add_f32_e32 v55, v69, v110
	v_mul_f32_e32 v55, 0xbfb8aa3b, v55
	v_exp_f32_e32 v55, v55
	s_waitcnt vmcnt(0)
	v_mfma_f32_16x16x32_bf16 v[114:117], v[16:19], v[32:35], v[114:117]
	ds_write_b16 v70, v54 offset:16928
	v_mul_f32_e32 v60, v94, v48
	v_add_f32_e32 v54, 1.0, v55
	v_rcp_f32_e32 v54, v54
	v_add_f32_e32 v61, v69, v111
	s_nop 2
	v_add_f32_e32 v55, v52, v114
	v_mul_f32_e32 v55, 0xbfb8aa3b, v55
	v_exp_f32_e32 v55, v55
	v_mul_f32_e32 v54, 0x3f1b4598, v54
	v_cvt_pk_bf16_f32 v60, v60, s0
	v_cvt_pk_bf16_f32 v54, v54, s0
	v_add_f32_e32 v55, 1.0, v55
	v_rcp_f32_e32 v55, v55
	v_mul_f32_e32 v61, 0xbfb8aa3b, v61
	ds_write_b16 v70, v60 offset:33824
	v_exp_f32_e32 v61, v61
	ds_write_b16 v71, v54 offset:64
	v_cvt_pk_bf16_f32 v54, v55, s0
	v_add_f32_e32 v55, v52, v115
	v_mul_f32_e32 v55, 0xbfb8aa3b, v55
	v_exp_f32_e32 v55, v55
	ds_write_b16 v71, v54 offset:16960
	v_add_f32_e32 v54, 1.0, v61
	v_rcp_f32_e32 v54, v54
	v_add_f32_e32 v55, 1.0, v55
	v_rcp_f32_e32 v55, v55
	v_mul_f32_e32 v60, v97, v105
	v_mul_f32_e32 v54, 0x3f1b4598, v54
	v_add_f32_e32 v61, v69, v112
	v_cvt_pk_bf16_f32 v60, v60, s0
	v_cvt_pk_bf16_f32 v54, v54, s0
	v_mul_f32_e32 v61, 0xbfb8aa3b, v61
	ds_write_b16 v71, v60 offset:33856
	v_exp_f32_e32 v61, v61
	ds_write_b16 v77, v54 offset:64
	v_cvt_pk_bf16_f32 v54, v55, s0
	v_add_f32_e32 v55, v52, v116
	v_mul_f32_e32 v55, 0xbfb8aa3b, v55
	v_exp_f32_e32 v55, v55
	ds_write_b16 v77, v54 offset:16960
	v_add_f32_e32 v54, 1.0, v61
	v_rcp_f32_e32 v54, v54
	v_add_f32_e32 v55, 1.0, v55
	v_add_f32_e32 v61, v69, v113
	v_rcp_f32_e32 v55, v55
	v_mul_f32_e32 v61, 0xbfb8aa3b, v61
	v_exp_f32_e32 v61, v61
	v_mul_f32_e32 v54, 0x3f1b4598, v54
	v_cvt_pk_bf16_f32 v54, v54, s0
	ds_write_b16 v132, v54 offset:64
	v_cvt_pk_bf16_f32 v54, v55, s0
	v_add_f32_e32 v55, v52, v117
	ds_write_b16 v132, v54 offset:16960
	v_add_f32_e32 v54, 1.0, v61
	v_mul_f32_e32 v55, 0xbfb8aa3b, v55
	v_rcp_f32_e32 v54, v54
	v_exp_f32_e32 v55, v55
	v_mul_f32_e32 v60, v93, v102
	v_cvt_pk_bf16_f32 v60, v60, s0
	v_mul_f32_e32 v54, 0x3f1b4598, v54
	v_add_f32_e32 v55, 1.0, v55
	ds_write_b16 v77, v60 offset:33856
	v_mul_f32_e32 v60, v91, v100
	v_rcp_f32_e32 v66, v55
	v_cvt_pk_bf16_f32 v67, v54, s0
	v_lshlrev_b64 v[54:55], 7, v[58:59]
	v_cvt_pk_bf16_f32 v60, v60, s0
	v_lshl_add_u64 v[62:63], v[62:63], 0, v[54:55]
	v_lshl_add_u64 v[54:55], v[64:65], 0, v[54:55]
	ds_write_b16 v132, v60 offset:33856
	v_mfma_f32_16x16x32_bf16 v[44:47], v[12:15], v[44:47], 0
	global_load_dwordx4 v[58:61], v[62:63], off
	global_load_dwordx4 v[96:99], v[62:63], off offset:64
	ds_write_b16 v133, v67 offset:64
	global_load_dwordx4 v[62:65], v[54:55], off
	v_mfma_f32_16x16x32_bf16 v[36:39], v[4:7], v[36:39], 0
	v_cvt_pk_bf16_f32 v77, v66, s0
	v_lshl_add_u64 v[66:67], s[70:71], 0, v[56:57]
	global_load_dword v66, v[66:67], off
	v_mfma_f32_16x16x32_bf16 v[44:47], v[8:11], v[106:109], v[44:47]
	global_load_dwordx4 v[106:109], v[54:55], off offset:64
	v_mul_f32_e32 v71, v89, v95
	ds_write_b16 v133, v77 offset:16960
	v_mfma_f32_16x16x32_bf16 v[32:35], v[0:3], v[32:35], v[36:39]
	s_ashr_i32 s42, s62, 31
	s_nop 2
	v_add_f32_e32 v44, v69, v44
	v_mul_f32_e32 v44, 0xbfb8aa3b, v44
	v_lshl_add_u64 v[36:37], s[74:75], 0, v[56:57]
	global_load_dword v36, v[36:37], off
	v_add_f32_e32 v32, v52, v32
	v_mul_f32_e32 v32, 0xbfb8aa3b, v32
	v_exp_f32_e32 v32, v32
	v_exp_f32_e32 v44, v44
	v_add_f32_e32 v39, v69, v45
	v_mul_f32_e32 v39, 0xbfb8aa3b, v39
	v_add_f32_e32 v32, 1.0, v32
	v_rcp_f32_e32 v32, v32
	v_exp_f32_e32 v39, v39
	v_add_f32_e32 v33, v52, v33
	v_mul_f32_e32 v33, 0xbfb8aa3b, v33
	v_add_f32_e32 v38, 1.0, v44
	v_exp_f32_e32 v33, v33
	v_rcp_f32_e32 v37, v38
	v_cvt_pk_bf16_f32 v32, v32, s0
	ds_write_b16 v51, v32 offset:16960
	v_add_f32_e32 v32, 1.0, v39
	v_rcp_f32_e32 v32, v32
	v_add_f32_e32 v33, 1.0, v33
	v_cvt_pk_bf16_f32 v38, v71, s0
	v_mul_f32_e32 v37, 0x3f1b4598, v37
	v_rcp_f32_e32 v33, v33
	ds_write_b16 v133, v38 offset:33856
	v_mul_f32_e32 v38, v82, v92
	v_cvt_pk_bf16_f32 v37, v37, s0
	ds_write_b16 v51, v37 offset:64
	v_cvt_pk_bf16_f32 v37, v38, s0
	v_mul_f32_e32 v32, 0x3f1b4598, v32
	v_add_f32_e32 v38, v69, v46
	v_cvt_pk_bf16_f32 v32, v32, s0
	v_mul_f32_e32 v38, 0xbfb8aa3b, v38
	v_exp_f32_e32 v38, v38
	ds_write_b16 v53, v32 offset:64
	v_cvt_pk_bf16_f32 v32, v33, s0
	v_add_f32_e32 v33, v52, v34
	v_mul_f32_e32 v33, 0xbfb8aa3b, v33
	v_exp_f32_e32 v33, v33
	ds_write_b16 v53, v32 offset:16960
	v_add_f32_e32 v32, 1.0, v38
	s_waitcnt vmcnt(5)
; __device__ __forceinline__ bf16_t f2bf(float f) { return (bf16_t)(pack2(f, 0.f) & 0xffffu); }
; __device__ __forceinline__ float sigmoidf_(float x) { return frcp(1.f + __expf(-x)); }
; #define MFMA(a, b, c) __builtin_amdgcn_mfma_f32_16x16x32_bf16(a, b, c, 0, 0, 0)
; __device__ __forceinline__ void rwkv_prep_tile(const Params& p, int l, int tile, unsigned char* smem) {
;     ...
;   for (int nt = 0; nt < 4; ++nt) {
;     const int c = w * 64 + nt * 16 + fr;
;     const bf16_t* wup = p.WupT + ((size_t)(ld2 * 256 + c)) * 64 + fq * 8;
;     const bf16_t* aup = p.AupT + ((size_t)(ld2 * 256 + c)) * 64 + fq * 8;
;     const bf16x8 bw0 = *(const bf16x8*)wup, bw1 = *(const bf16x8*)(wup + 32);
;     const bf16x8 ba0 = *(const bf16x8*)aup, ba1 = *(const bf16x8*)(aup + 32);
;     const float w0c = p.rwkv_w0[ld2 * 256 + c], a0c = p.rwkv_a0[ld2 * 256 + c];
; #pragma unroll
;     for (int mt = 0; mt < 2; ++mt) {
;       f32x4 accw = (f32x4){0.f, 0.f, 0.f, 0.f}, acca = (f32x4){0.f, 0.f, 0.f, 0.f};
;       accw = MFMA(aw[mt][0], bw0, accw);
;       accw = MFMA(aw[mt][1], bw1, accw);
;       acca = MFMA(aa[mt][0], ba0, acca);
;       acca = MFMA(aa[mt][1], ba1, acca);
; #pragma unroll
;       for (int j = 0; j < 4; ++j) {
;         const int i = mt * 16 + fq * 4 + j;
;         const float ew = 0.6065306597f * sigmoidf_(w0c + accw[j]);
;         const float a = sigmoidf_(a0c + acca[j]);
;         const float kk = kkr[mt][nt][j] * inv[mt][j];
;         bf16_t* o = stg + i * 264 + c;
;         o[0] = f2bf(ew);
;         o[32 * 264] = f2bf(a);
;         o[2 * 32 * 264] = f2bf(kk);
;       }
;     }
;   }
;   __syncthreads();
; #pragma unroll
;   for (int t = 0; t < 12; ++t) {
;     const int q = tid + 256 * t;
;     const int arr = q >> 10, i = (q >> 5) & 31, ch = q & 31;
;     const uint4 v = *(const uint4*)(stg + (arr * 32 + i) * 264 + ch * 8);
;     *(uint4*)(p.PRE + (size_t)arr * PRE_ARR + ((rowbase + p0 + i) * 2 + d) * 256 + ch * 8) = v;
	v_mfma_f32_16x16x32_bf16 v[28:31], v[28:31], v[58:61], 0
	v_rcp_f32_e32 v32, v32
	v_add_f32_e32 v33, 1.0, v33
	v_rcp_f32_e32 v33, v33
	s_waitcnt vmcnt(3)
	v_mfma_f32_16x16x32_bf16 v[20:23], v[20:23], v[62:65], 0
	v_mul_f32_e32 v32, 0x3f1b4598, v32
	ds_write_b16 v51, v37 offset:33856
	v_mul_f32_e32 v37, v80, v90
	v_mfma_f32_16x16x32_bf16 v[24:27], v[24:27], v[96:99], v[28:31]
	v_cvt_pk_bf16_f32 v32, v32, s0
	v_cvt_pk_bf16_f32 v34, v37, s0
	v_add_f32_e32 v37, v69, v47
	s_waitcnt vmcnt(1)
	v_mfma_f32_16x16x32_bf16 v[16:19], v[16:19], v[106:109], v[20:23]
	ds_write_b16 v134, v32 offset:64
	v_cvt_pk_bf16_f32 v32, v33, s0
	v_add_f32_e32 v33, v52, v35
	v_mul_f32_e32 v37, 0xbfb8aa3b, v37
	v_mul_f32_e32 v33, 0xbfb8aa3b, v33
	v_add_f32_e32 v24, v66, v24
	s_waitcnt vmcnt(0)
	s_nop 0
	v_add_f32_e32 v16, v36, v16
	v_exp_f32_e32 v37, v37
	v_exp_f32_e32 v33, v33
	v_mul_f32_e32 v24, 0xbfb8aa3b, v24
	v_mul_f32_e32 v16, 0xbfb8aa3b, v16
	v_exp_f32_e32 v24, v24
	v_exp_f32_e32 v16, v16
	ds_write_b16 v134, v32 offset:16960
	v_add_f32_e32 v32, 1.0, v37
	v_add_f32_e32 v33, 1.0, v33
	v_rcp_f32_e32 v32, v32
	v_rcp_f32_e32 v33, v33
	v_add_f32_e32 v20, 1.0, v24
	v_add_f32_e32 v16, 1.0, v16
	v_add_f32_e32 v24, v66, v25
	v_rcp_f32_e32 v16, v16
	v_mul_f32_e32 v24, 0xbfb8aa3b, v24
	ds_write_b16 v53, v34 offset:33856
	v_mul_f32_e32 v34, v79, v68
	v_exp_f32_e32 v24, v24
	v_add_f32_e32 v17, v36, v17
	v_mfma_f32_16x16x32_bf16 v[4:7], v[4:7], v[62:65], 0
	v_cvt_pk_bf16_f32 v34, v34, s0
	v_mul_f32_e32 v17, 0xbfb8aa3b, v17
	ds_write_b16 v134, v34 offset:33856
	v_mul_f32_e32 v32, 0x3f1b4598, v32
	v_mul_f32_e32 v34, v85, v48
	v_cvt_pk_bf16_f32 v28, v33, s0
	v_rcp_f32_e32 v20, v20
	v_add_u32_e32 v21, 0, v75
	v_exp_f32_e32 v17, v17
	v_cvt_pk_bf16_f32 v32, v32, s0
	ds_write_b16 v70, v28 offset:16960
	v_cvt_pk_bf16_f32 v28, v34, s0
	v_mad_u32_u24 v23, v73, s0, v21
	v_cvt_pk_bf16_f32 v16, v16, s0
	v_mfma_f32_16x16x32_bf16 v[12:15], v[12:15], v[58:61], 0
	ds_write_b16 v70, v32 offset:64
	ds_write_b16 v70, v28 offset:33856
	ds_write_b16 v23, v16 offset:16896
	v_add_f32_e32 v16, 1.0, v24
	v_mfma_f32_16x16x32_bf16 v[0:3], v[0:3], v[106:109], v[4:7]
	v_rcp_f32_e32 v16, v16
	v_mul_f32_e32 v20, 0x3f1b4598, v20
	v_add_f32_e32 v17, 1.0, v17
	v_mul_f32_e32 v22, v83, v105
	v_cvt_pk_bf16_f32 v20, v20, s0
	v_rcp_f32_e32 v17, v17
	v_mfma_f32_16x16x32_bf16 v[8:11], v[8:11], v[96:99], v[12:15]
	ds_write_b16 v23, v20
	v_cvt_pk_bf16_f32 v20, v22, s0
	v_add_f32_e32 v0, v36, v0
	ds_write_b16 v23, v20 offset:33792
	v_mul_f32_e32 v16, 0x3f1b4598, v16
	v_add_f32_e32 v23, v66, v26
	v_mul_f32_e32 v0, 0xbfb8aa3b, v0
	v_mad_u32_u24 v22, v74, s56, v21
	v_cvt_pk_bf16_f32 v16, v16, s0
	v_mul_f32_e32 v23, 0xbfb8aa3b, v23
	v_exp_f32_e32 v0, v0
	v_exp_f32_e32 v23, v23
	ds_write_b16 v22, v16
	v_cvt_pk_bf16_f32 v16, v17, s0
	v_add_f32_e32 v17, v36, v18
	v_add_f32_e32 v8, v66, v8
	v_mul_f32_e32 v17, 0xbfb8aa3b, v17
	v_mul_f32_e32 v8, 0xbfb8aa3b, v8
	v_exp_f32_e32 v17, v17
	v_exp_f32_e32 v8, v8
	v_add_f32_e32 v0, 1.0, v0
	v_add_f32_e32 v7, v66, v9
	ds_write_b16 v22, v16 offset:16896
	v_add_f32_e32 v16, 1.0, v23
	v_rcp_f32_e32 v0, v0
	v_mul_f32_e32 v7, 0xbfb8aa3b, v7
	v_rcp_f32_e32 v16, v16
	v_exp_f32_e32 v7, v7
	v_add_f32_e32 v1, v36, v1
	v_mul_f32_e32 v20, v81, v102
	v_add_f32_e32 v17, 1.0, v17
	v_add_f32_e32 v4, 1.0, v8
	v_mul_f32_e32 v1, 0xbfb8aa3b, v1
	v_cvt_pk_bf16_f32 v18, v20, s0
	v_rcp_f32_e32 v17, v17
	v_rcp_f32_e32 v4, v4
	v_exp_f32_e32 v1, v1
	ds_write_b16 v22, v18 offset:33792
	v_mul_f32_e32 v18, v78, v100
	v_add_u32_e32 v6, v21, v43
	v_cvt_pk_bf16_f32 v0, v0, s0
	v_mul_f32_e32 v16, 0x3f1b4598, v16
	v_add_u32_e32 v20, v21, v50
	v_cvt_pk_bf16_f32 v18, v18, s0
	ds_write_b16 v6, v0 offset:16896
	v_add_f32_e32 v0, 1.0, v7
	v_cvt_pk_bf16_f32 v16, v16, s0
	ds_write_b16 v20, v18 offset:33792
	v_mul_f32_e32 v18, v76, v95
	v_rcp_f32_e32 v0, v0
	ds_write_b16 v20, v16
	v_cvt_pk_bf16_f32 v16, v17, s0
	v_add_f32_e32 v17, v36, v19
	v_add_u32_e32 v19, v21, v49
	v_cvt_pk_bf16_f32 v5, v18, s0
	v_mul_f32_e32 v4, 0x3f1b4598, v4
	v_add_f32_e32 v1, 1.0, v1
	ds_write_b16 v19, v5 offset:33792
	v_mul_f32_e32 v5, v88, v92
	v_cvt_pk_bf16_f32 v4, v4, s0
	v_rcp_f32_e32 v1, v1
	ds_write_b16 v6, v4
	v_cvt_pk_bf16_f32 v4, v5, s0
	ds_write_b16 v6, v4 offset:33792
	v_mul_f32_e32 v0, 0x3f1b4598, v0
	v_add_f32_e32 v6, v66, v10
	v_add_u32_e32 v5, v21, v42
	v_cvt_pk_bf16_f32 v0, v0, s0
	v_mul_f32_e32 v6, 0xbfb8aa3b, v6
	v_exp_f32_e32 v6, v6
	ds_write_b16 v5, v0
	v_cvt_pk_bf16_f32 v0, v1, s0
	v_add_f32_e32 v1, v36, v2
	v_mul_f32_e32 v1, 0xbfb8aa3b, v1
	v_exp_f32_e32 v1, v1
	ds_write_b16 v5, v0 offset:16896
	v_add_f32_e32 v0, 1.0, v6
	v_rcp_f32_e32 v0, v0
	v_add_f32_e32 v1, 1.0, v1
	v_mul_f32_e32 v4, v87, v90
	v_rcp_f32_e32 v1, v1
	v_cvt_pk_bf16_f32 v2, v4, s0
	ds_write_b16 v5, v2 offset:33792
	v_mul_f32_e32 v0, 0x3f1b4598, v0
	v_add_f32_e32 v5, v66, v11
	v_add_f32_e32 v22, v66, v27
	v_add_u32_e32 v4, v21, v41
	v_cvt_pk_bf16_f32 v0, v0, s0
	v_mul_f32_e32 v5, 0xbfb8aa3b, v5
	v_mul_f32_e32 v22, 0xbfb8aa3b, v22
	v_exp_f32_e32 v5, v5
	ds_write_b16 v4, v0
	v_cvt_pk_bf16_f32 v0, v1, s0
	v_add_f32_e32 v1, v36, v3
	v_exp_f32_e32 v22, v22
	v_mul_f32_e32 v1, 0xbfb8aa3b, v1
	v_mul_f32_e32 v17, 0xbfb8aa3b, v17
	v_exp_f32_e32 v1, v1
	v_exp_f32_e32 v17, v17
	ds_write_b16 v4, v0 offset:16896
	v_add_f32_e32 v0, 1.0, v5
	ds_write_b16 v20, v16 offset:16896
	v_add_f32_e32 v16, 1.0, v22
	v_rcp_f32_e32 v0, v0
	v_rcp_f32_e32 v16, v16
	v_add_f32_e32 v1, 1.0, v1
	v_add_f32_e32 v17, 1.0, v17
	v_rcp_f32_e32 v1, v1
	v_rcp_f32_e32 v17, v17
	v_mul_f32_e32 v2, v86, v68
	v_mul_f32_e32 v0, 0x3f1b4598, v0
	v_mul_f32_e32 v16, 0x3f1b4598, v16
	v_cvt_pk_bf16_f32 v2, v2, s0
	v_add_u32_e32 v3, v21, v40
	v_cvt_pk_bf16_f32 v0, v0, s0
	v_cvt_pk_bf16_f32 v12, v16, s0
	ds_write_b16 v4, v2 offset:33792
	v_mul_f32_e32 v2, v84, v48
	ds_write_b16 v3, v0
	v_cvt_pk_bf16_f32 v0, v1, s0
	ds_write_b16 v19, v12
	v_cvt_pk_bf16_f32 v12, v17, s0
	ds_write_b16 v3, v0 offset:16896
	v_cvt_pk_bf16_f32 v0, v2, s0
	s_add_u32 s44, s44, s62
	v_readlane_b32 s0, v252, 0
	ds_write_b16 v3, v0 offset:33792
	v_lshlrev_b32_e32 v0, 4, v72
	s_addc_u32 s45, s45, s42
	v_bfe_u32 v11, v72, 5, 5
	v_readlane_b32 s4, v252, 4
	v_readlane_b32 s5, v252, 5
	ds_write_b16 v19, v12 offset:16896
	v_and_b32_e32 v8, 0x1f0, v0
	v_ashrrev_i32_e32 v4, 10, v72
	v_mov_b64_e32 v[12:13], s[4:5]
	s_mov_b32 s0, 0x1100000
	v_or_b32_e32 v14, s44, v11
	v_mov_b32_e32 v15, s45
	v_add_u32_e32 v10, 0, v8
	v_lshl_or_b32 v0, v4, 5, v11
	v_mad_i64_i32 v[4:5], s[42:43], v4, s0, v[12:13]
	v_lshlrev_b64 v[16:17], 10, v[14:15]
	v_mad_u64_u32 v[0:1], s[42:43], v0, s56, v[10:11]
	v_lshl_add_u64 v[4:5], v[4:5], 0, v[16:17]
	s_lshl_b32 s28, s28, 9
	s_waitcnt lgkmcnt(0)
	s_barrier
; __device__ __forceinline__ void rwkv_prep_tile(const Params& p, int l, int tile, unsigned char* smem) {
;     ...
; #pragma unroll
;   for (int t = 0; t < 12; ++t) {
;     const int q = tid + 256 * t;
;     const int arr = q >> 10, i = (q >> 5) & 31, ch = q & 31;
;     const uint4 v = *(const uint4*)(stg + (arr * 32 + i) * 264 + ch * 8);
;     *(uint4*)(p.PRE + (size_t)arr * PRE_ARR + ((rowbase + p0 + i) * 2 + d) * 256 + ch * 8) = v;
;   }
;   __syncthreads();
	ds_read_b128 v[0:3], v0
	v_lshl_add_u64 v[4:5], v[4:5], 0, s[28:29]
	v_mov_b32_e32 v9, v164
	v_lshl_add_u64 v[18:19], v[4:5], 0, v[8:9]
	v_add_u32_e32 v4, 0x100, v72
	v_ashrrev_i32_e32 v14, 10, v4
	v_bfe_u32 v20, v4, 5, 5
	v_lshl_or_b32 v4, v14, 5, v20
	v_mad_u64_u32 v[4:5], s[42:43], v4, s56, v[10:11]
	ds_read_b128 v[4:7], v4
	s_waitcnt lgkmcnt(1)
	global_store_dwordx4 v[18:19], v[0:3], off
	v_readlane_b32 s1, v252, 1
	v_readlane_b32 s2, v252, 2
	v_mad_i64_i32 v[0:1], s[42:43], v14, s0, v[12:13]
	v_or_b32_e32 v14, s44, v20
	v_lshlrev_b64 v[2:3], 10, v[14:15]
	v_lshl_add_u64 v[0:1], v[0:1], 0, v[2:3]
	v_lshl_add_u64 v[0:1], v[0:1], 0, s[28:29]
	v_lshl_add_u64 v[0:1], v[0:1], 0, v[8:9]
	s_waitcnt lgkmcnt(0)
	global_store_dwordx4 v[0:1], v[4:7], off
	v_add_u32_e32 v0, 0x200, v72
	v_readlane_b32 s3, v252, 3
	v_bfe_u32 v6, v0, 5, 5
	v_ashrrev_i32_e32 v4, 10, v0
	v_or_b32_e32 v14, s44, v6
	v_lshl_or_b32 v0, v4, 5, v6
	v_mad_i64_i32 v[4:5], s[42:43], v4, s0, v[12:13]
	v_lshlrev_b64 v[6:7], 10, v[14:15]
	v_mad_u64_u32 v[0:1], s[42:43], v0, s56, v[10:11]
	v_lshl_add_u64 v[4:5], v[4:5], 0, v[6:7]
	ds_read_b128 v[0:3], v0
	v_lshl_add_u64 v[4:5], v[4:5], 0, s[28:29]
	v_lshl_add_u64 v[18:19], v[4:5], 0, v[8:9]
	v_add_u32_e32 v4, 0x300, v72
	v_ashrrev_i32_e32 v14, 10, v4
	v_bfe_u32 v20, v4, 5, 5
	v_lshl_or_b32 v4, v14, 5, v20
	v_mad_u64_u32 v[4:5], s[42:43], v4, s56, v[10:11]
	ds_read_b128 v[4:7], v4
	s_waitcnt lgkmcnt(1)
	global_store_dwordx4 v[18:19], v[0:3], off
	v_readlane_b32 s6, v252, 6
	v_readlane_b32 s7, v252, 7
	v_mad_i64_i32 v[0:1], s[42:43], v14, s0, v[12:13]
	v_or_b32_e32 v14, s44, v20
	v_lshlrev_b64 v[2:3], 10, v[14:15]
	v_lshl_add_u64 v[0:1], v[0:1], 0, v[2:3]
	v_lshl_add_u64 v[0:1], v[0:1], 0, s[28:29]
	v_lshl_add_u64 v[0:1], v[0:1], 0, v[8:9]
	s_waitcnt lgkmcnt(0)
	global_store_dwordx4 v[0:1], v[4:7], off
	v_add_u32_e32 v0, 0x400, v72
	v_readlane_b32 s8, v252, 8
	v_ashrrev_i32_e32 v4, 10, v0
	v_lshl_or_b32 v0, v4, 5, v11
	v_mad_i64_i32 v[4:5], s[42:43], v4, s0, v[12:13]
	v_mad_u64_u32 v[0:1], s[42:43], v0, s56, v[10:11]
	v_lshl_add_u64 v[4:5], v[4:5], 0, v[16:17]
	ds_read_b128 v[0:3], v0
	v_lshl_add_u64 v[4:5], v[4:5], 0, s[28:29]
	v_lshl_add_u64 v[18:19], v[4:5], 0, v[8:9]
	v_add_u32_e32 v4, 0x500, v72
	v_ashrrev_i32_e32 v14, 10, v4
	v_bfe_u32 v20, v4, 5, 5
	v_lshl_or_b32 v4, v14, 5, v20
	v_mad_u64_u32 v[4:5], s[42:43], v4, s56, v[10:11]
	ds_read_b128 v[4:7], v4
	s_waitcnt lgkmcnt(1)
	global_store_dwordx4 v[18:19], v[0:3], off
	v_readlane_b32 s9, v252, 9
	v_readlane_b32 s10, v252, 10
	v_mad_i64_i32 v[0:1], s[42:43], v14, s0, v[12:13]
	v_or_b32_e32 v14, s44, v20
	v_lshlrev_b64 v[2:3], 10, v[14:15]
	v_lshl_add_u64 v[0:1], v[0:1], 0, v[2:3]
	v_lshl_add_u64 v[0:1], v[0:1], 0, s[28:29]
	v_lshl_add_u64 v[0:1], v[0:1], 0, v[8:9]
	s_waitcnt lgkmcnt(0)
	global_store_dwordx4 v[0:1], v[4:7], off
	v_add_u32_e32 v0, 0x600, v72
	v_readlane_b32 s11, v252, 11
	v_bfe_u32 v6, v0, 5, 5
	v_ashrrev_i32_e32 v4, 10, v0
	v_or_b32_e32 v14, s44, v6
	v_lshl_or_b32 v0, v4, 5, v6
	v_mad_i64_i32 v[4:5], s[42:43], v4, s0, v[12:13]
	v_lshlrev_b64 v[6:7], 10, v[14:15]
	v_mad_u64_u32 v[0:1], s[42:43], v0, s56, v[10:11]
	v_lshl_add_u64 v[4:5], v[4:5], 0, v[6:7]
	ds_read_b128 v[0:3], v0
	v_lshl_add_u64 v[4:5], v[4:5], 0, s[28:29]
	v_lshl_add_u64 v[18:19], v[4:5], 0, v[8:9]
	v_add_u32_e32 v4, 0x700, v72
	v_ashrrev_i32_e32 v14, 10, v4
	v_bfe_u32 v20, v4, 5, 5
	v_lshl_or_b32 v4, v14, 5, v20
	v_mad_u64_u32 v[4:5], s[42:43], v4, s56, v[10:11]
	ds_read_b128 v[4:7], v4
	s_waitcnt lgkmcnt(1)
	global_store_dwordx4 v[18:19], v[0:3], off
	v_readlane_b32 s12, v252, 12
	v_readlane_b32 s13, v252, 13
	v_mad_i64_i32 v[0:1], s[42:43], v14, s0, v[12:13]
	v_or_b32_e32 v14, s44, v20
	v_lshlrev_b64 v[2:3], 10, v[14:15]
	v_lshl_add_u64 v[0:1], v[0:1], 0, v[2:3]
	v_lshl_add_u64 v[0:1], v[0:1], 0, s[28:29]
	v_lshl_add_u64 v[0:1], v[0:1], 0, v[8:9]
	s_waitcnt lgkmcnt(0)
	global_store_dwordx4 v[0:1], v[4:7], off
	v_add_u32_e32 v0, 0x800, v72
	v_readlane_b32 s14, v252, 14
	v_ashrrev_i32_e32 v4, 10, v0
	v_lshl_or_b32 v0, v4, 5, v11
	v_mad_i64_i32 v[4:5], s[42:43], v4, s0, v[12:13]
	v_lshl_add_u64 v[4:5], v[4:5], 0, v[16:17]
	v_mad_u64_u32 v[0:1], s[42:43], v0, s56, v[10:11]
	v_lshl_add_u64 v[4:5], v[4:5], 0, s[28:29]
	ds_read_b128 v[0:3], v0
	v_lshl_add_u64 v[16:17], v[4:5], 0, v[8:9]
	v_add_u32_e32 v4, 0x900, v72
	v_ashrrev_i32_e32 v11, 10, v4
	v_bfe_u32 v14, v4, 5, 5
	v_lshl_or_b32 v4, v11, 5, v14
	v_mad_u64_u32 v[4:5], s[42:43], v4, s56, v[10:11]
	ds_read_b128 v[4:7], v4
	v_or_b32_e32 v14, s44, v14
	s_waitcnt lgkmcnt(1)
	global_store_dwordx4 v[16:17], v[0:3], off
	v_readlane_b32 s15, v252, 15
	s_nop 0
	v_mad_i64_i32 v[0:1], s[42:43], v11, s0, v[12:13]
	v_lshlrev_b64 v[2:3], 10, v[14:15]
	v_lshl_add_u64 v[0:1], v[0:1], 0, v[2:3]
	v_lshl_add_u64 v[0:1], v[0:1], 0, s[28:29]
	v_lshl_add_u64 v[0:1], v[0:1], 0, v[8:9]
	s_waitcnt lgkmcnt(0)
	global_store_dwordx4 v[0:1], v[4:7], off
	v_add_u32_e32 v0, 0xa00, v72
	s_nop 0
	v_bfe_u32 v6, v0, 5, 5
	v_ashrrev_i32_e32 v4, 10, v0
	v_or_b32_e32 v14, s44, v6
	v_lshl_or_b32 v0, v4, 5, v6
	v_mad_i64_i32 v[4:5], s[42:43], v4, s0, v[12:13]
	v_lshlrev_b64 v[6:7], 10, v[14:15]
	v_lshl_add_u64 v[4:5], v[4:5], 0, v[6:7]
	v_mad_u64_u32 v[0:1], s[42:43], v0, s56, v[10:11]
	v_lshl_add_u64 v[4:5], v[4:5], 0, s[28:29]
	ds_read_b128 v[0:3], v0
	v_lshl_add_u64 v[16:17], v[4:5], 0, v[8:9]
	v_add_u32_e32 v4, 0xb00, v72
	v_ashrrev_i32_e32 v11, 10, v4
	v_bfe_u32 v14, v4, 5, 5
	v_lshl_or_b32 v4, v11, 5, v14
	v_mad_u64_u32 v[4:5], s[42:43], v4, s56, v[10:11]
	ds_read_b128 v[4:7], v4
	v_or_b32_e32 v14, s44, v14
	s_waitcnt lgkmcnt(1)
	global_store_dwordx4 v[16:17], v[0:3], off
	s_nop 1
	v_mad_i64_i32 v[0:1], s[42:43], v11, s0, v[12:13]
	v_lshlrev_b64 v[2:3], 10, v[14:15]
	v_lshl_add_u64 v[0:1], v[0:1], 0, v[2:3]
	v_lshl_add_u64 v[0:1], v[0:1], 0, s[28:29]
	v_lshl_add_u64 v[0:1], v[0:1], 0, v[8:9]
	s_waitcnt lgkmcnt(0)
	global_store_dwordx4 v[0:1], v[4:7], off
	s_barrier
	s_branch .LBB0_596

; template <int MODE>
; __device__ __forceinline__ void gemm_tile(const Params& p, int l, int mt_, int nt_, unsigned char* smem) {
;     ...
; #pragma unroll
;       for (int t = 0; t < 16; ++t) {
;         const int rl = (lane >> 4) + 4 * t;
;         const float4 a4 = *(const float4*)(wbuf + rl * 68 + ch * 4);
;         const float4 r4 = *(const float4*)(resb + (size_t)rl * 1024 + cbase + ch * 4);
;         float4 o4;
;         o4.x = r4.x + g4.x * a4.x; o4.y = r4.y + g4.y * a4.y; o4.z = r4.z + g4.z * a4.z; o4.w = r4.w + g4.w * a4.w;
;         *(float4*)(dstb + (size_t)rl * 1024 + cbase + ch * 4) = o4;
;       }
.LBB0_1292:
	v_mov_b32_e32 v7, v164
	v_lshl_add_u64 v[4:5], v[10:11], 0, v[6:7]
	v_mov_b32_e32 v9, v164
	v_lshl_add_u64 v[6:7], v[12:13], 0, v[6:7]
	v_lshl_add_u64 v[4:5], v[4:5], 0, v[8:9]
	v_lshl_add_u64 v[6:7], v[6:7], 0, v[8:9]
	v_mul_u32_u24_e32 v9, 0x110, v80
	v_add3_u32 v10, v14, v8, v9
	v_lshlrev_b32_e32 v8, 12, v80
	v_mov_b32_e32 v9, v164
	v_mov_b32_e32 v105, v164
	v_lshl_add_u64 v[106:107], v[4:5], 0, v[8:9]
	global_load_dwordx4 v[16:19], v[106:107], off
	v_or_b32_e32 v104, 0x4000, v8
	v_lshl_add_u64 v[106:107], v[4:5], 0, v[104:105]
	global_load_dwordx4 v[20:23], v[106:107], off
	v_or_b32_e32 v104, 0x8000, v8
	v_lshl_add_u64 v[106:107], v[4:5], 0, v[104:105]
	global_load_dwordx4 v[24:27], v[106:107], off
	v_or_b32_e32 v104, 0xc000, v8
	v_lshl_add_u64 v[106:107], v[4:5], 0, v[104:105]
	global_load_dwordx4 v[28:31], v[106:107], off
	v_or_b32_e32 v104, 0x10000, v8
	v_lshl_add_u64 v[106:107], v[4:5], 0, v[104:105]
	global_load_dwordx4 v[32:35], v[106:107], off
	v_or_b32_e32 v104, 0x14000, v8
	v_lshl_add_u64 v[106:107], v[4:5], 0, v[104:105]
	global_load_dwordx4 v[36:39], v[106:107], off
	v_or_b32_e32 v104, 0x18000, v8
	v_lshl_add_u64 v[106:107], v[4:5], 0, v[104:105]
	global_load_dwordx4 v[40:43], v[106:107], off
	v_or_b32_e32 v104, 0x1c000, v8
	v_lshl_add_u64 v[106:107], v[4:5], 0, v[104:105]
	global_load_dwordx4 v[44:47], v[106:107], off
	v_or_b32_e32 v104, 0x20000, v8
	v_lshl_add_u64 v[106:107], v[4:5], 0, v[104:105]
	global_load_dwordx4 v[48:51], v[106:107], off
	v_or_b32_e32 v104, 0x24000, v8
	v_lshl_add_u64 v[106:107], v[4:5], 0, v[104:105]
	global_load_dwordx4 v[52:55], v[106:107], off
	v_or_b32_e32 v104, 0x28000, v8
	v_lshl_add_u64 v[106:107], v[4:5], 0, v[104:105]
	global_load_dwordx4 v[56:59], v[106:107], off
	v_or_b32_e32 v104, 0x2c000, v8
	v_lshl_add_u64 v[106:107], v[4:5], 0, v[104:105]
	global_load_dwordx4 v[60:63], v[106:107], off
	v_or_b32_e32 v104, 0x30000, v8
	v_lshl_add_u64 v[106:107], v[4:5], 0, v[104:105]
	global_load_dwordx4 v[64:67], v[106:107], off
	v_or_b32_e32 v104, 0x34000, v8
	v_lshl_add_u64 v[106:107], v[4:5], 0, v[104:105]
	global_load_dwordx4 v[68:71], v[106:107], off
	v_or_b32_e32 v104, 0x38000, v8
	v_lshl_add_u64 v[106:107], v[4:5], 0, v[104:105]
	global_load_dwordx4 v[72:75], v[106:107], off
	v_or_b32_e32 v104, 0x3c000, v8
	v_lshl_add_u64 v[106:107], v[4:5], 0, v[104:105]
	global_load_dwordx4 v[76:79], v[106:107], off
	ds_read_b128 v[84:87], v10
	ds_read_b128 v[88:91], v10 offset:1088
	ds_read_b128 v[92:95], v10 offset:2176
	ds_read_b128 v[96:99], v10 offset:3264
	s_waitcnt vmcnt(0) lgkmcnt(0)
	v_pk_fma_f32 v[84:85], v[0:1], v[84:85], v[16:17]
	v_pk_fma_f32 v[86:87], v[2:3], v[86:87], v[18:19]
	v_pk_fma_f32 v[88:89], v[0:1], v[88:89], v[20:21]
	v_pk_fma_f32 v[90:91], v[2:3], v[90:91], v[22:23]
	v_pk_fma_f32 v[92:93], v[0:1], v[92:93], v[24:25]
	v_pk_fma_f32 v[94:95], v[2:3], v[94:95], v[26:27]
	v_pk_fma_f32 v[96:97], v[0:1], v[96:97], v[28:29]
	v_pk_fma_f32 v[98:99], v[2:3], v[98:99], v[30:31]
	v_lshl_add_u64 v[106:107], v[6:7], 0, v[8:9]
	global_store_dwordx4 v[106:107], v[84:87], off
	v_or_b32_e32 v104, 0x4000, v8
	v_lshl_add_u64 v[106:107], v[6:7], 0, v[104:105]
	global_store_dwordx4 v[106:107], v[88:91], off
	v_or_b32_e32 v104, 0x8000, v8
	v_lshl_add_u64 v[106:107], v[6:7], 0, v[104:105]
	global_store_dwordx4 v[106:107], v[92:95], off
	v_or_b32_e32 v104, 0xc000, v8
	v_lshl_add_u64 v[106:107], v[6:7], 0, v[104:105]
	global_store_dwordx4 v[106:107], v[96:99], off
	s_nop 1
	ds_read_b128 v[84:87], v10 offset:4352
	ds_read_b128 v[88:91], v10 offset:5440
	ds_read_b128 v[92:95], v10 offset:6528
	ds_read_b128 v[96:99], v10 offset:7616
	s_waitcnt lgkmcnt(0)
	v_pk_fma_f32 v[84:85], v[0:1], v[84:85], v[32:33]
	v_pk_fma_f32 v[86:87], v[2:3], v[86:87], v[34:35]
	v_pk_fma_f32 v[88:89], v[0:1], v[88:89], v[36:37]
	v_pk_fma_f32 v[90:91], v[2:3], v[90:91], v[38:39]
	v_pk_fma_f32 v[92:93], v[0:1], v[92:93], v[40:41]
	v_pk_fma_f32 v[94:95], v[2:3], v[94:95], v[42:43]
	v_pk_fma_f32 v[96:97], v[0:1], v[96:97], v[44:45]
	v_pk_fma_f32 v[98:99], v[2:3], v[98:99], v[46:47]
	v_or_b32_e32 v104, 0x10000, v8
	v_lshl_add_u64 v[106:107], v[6:7], 0, v[104:105]
	global_store_dwordx4 v[106:107], v[84:87], off
	v_or_b32_e32 v104, 0x14000, v8
	v_lshl_add_u64 v[106:107], v[6:7], 0, v[104:105]
	global_store_dwordx4 v[106:107], v[88:91], off
	v_or_b32_e32 v104, 0x18000, v8
	v_lshl_add_u64 v[106:107], v[6:7], 0, v[104:105]
	global_store_dwordx4 v[106:107], v[92:95], off
	v_or_b32_e32 v104, 0x1c000, v8
	v_lshl_add_u64 v[106:107], v[6:7], 0, v[104:105]
	global_store_dwordx4 v[106:107], v[96:99], off
	s_nop 1
	ds_read_b128 v[84:87], v10 offset:8704
	ds_read_b128 v[88:91], v10 offset:9792
	ds_read_b128 v[92:95], v10 offset:10880
	ds_read_b128 v[96:99], v10 offset:11968
	s_waitcnt lgkmcnt(0)
	v_pk_fma_f32 v[84:85], v[0:1], v[84:85], v[48:49]
	v_pk_fma_f32 v[86:87], v[2:3], v[86:87], v[50:51]
	v_pk_fma_f32 v[88:89], v[0:1], v[88:89], v[52:53]
	v_pk_fma_f32 v[90:91], v[2:3], v[90:91], v[54:55]
	v_pk_fma_f32 v[92:93], v[0:1], v[92:93], v[56:57]
	v_pk_fma_f32 v[94:95], v[2:3], v[94:95], v[58:59]
	v_pk_fma_f32 v[96:97], v[0:1], v[96:97], v[60:61]
	v_pk_fma_f32 v[98:99], v[2:3], v[98:99], v[62:63]
	v_or_b32_e32 v104, 0x20000, v8
	v_lshl_add_u64 v[106:107], v[6:7], 0, v[104:105]
	global_store_dwordx4 v[106:107], v[84:87], off
	v_or_b32_e32 v104, 0x24000, v8
	v_lshl_add_u64 v[106:107], v[6:7], 0, v[104:105]
	global_store_dwordx4 v[106:107], v[88:91], off
	v_or_b32_e32 v104, 0x28000, v8
	v_lshl_add_u64 v[106:107], v[6:7], 0, v[104:105]
	global_store_dwordx4 v[106:107], v[92:95], off
	v_or_b32_e32 v104, 0x2c000, v8
	v_lshl_add_u64 v[106:107], v[6:7], 0, v[104:105]
	global_store_dwordx4 v[106:107], v[96:99], off
	s_nop 1
	ds_read_b128 v[84:87], v10 offset:13056
	ds_read_b128 v[88:91], v10 offset:14144
	ds_read_b128 v[92:95], v10 offset:15232
	ds_read_b128 v[96:99], v10 offset:16320
	s_waitcnt lgkmcnt(0)
	v_pk_fma_f32 v[84:85], v[0:1], v[84:85], v[64:65]
	v_pk_fma_f32 v[86:87], v[2:3], v[86:87], v[66:67]
	v_pk_fma_f32 v[88:89], v[0:1], v[88:89], v[68:69]
	v_pk_fma_f32 v[90:91], v[2:3], v[90:91], v[70:71]
	v_pk_fma_f32 v[92:93], v[0:1], v[92:93], v[72:73]
	v_pk_fma_f32 v[94:95], v[2:3], v[94:95], v[74:75]
	v_pk_fma_f32 v[96:97], v[0:1], v[96:97], v[76:77]
	v_pk_fma_f32 v[98:99], v[2:3], v[98:99], v[78:79]
	v_or_b32_e32 v104, 0x30000, v8
	v_lshl_add_u64 v[106:107], v[6:7], 0, v[104:105]
	global_store_dwordx4 v[106:107], v[84:87], off
	v_or_b32_e32 v104, 0x34000, v8
	v_lshl_add_u64 v[106:107], v[6:7], 0, v[104:105]
	global_store_dwordx4 v[106:107], v[88:91], off
	v_or_b32_e32 v104, 0x38000, v8
	v_lshl_add_u64 v[106:107], v[6:7], 0, v[104:105]
	global_store_dwordx4 v[106:107], v[92:95], off
	v_or_b32_e32 v104, 0x3c000, v8
	v_lshl_add_u64 v[106:107], v[6:7], 0, v[104:105]
	global_store_dwordx4 v[106:107], v[96:99], off
	s_nop 1
	s_barrier
